# GEMM loops: opening barrier of each MFMA segment issued after the first 3 MFMAs; A-fragment ds_reads before the LDS-DMA loads
# baseline (speedup 1.0000x reference)
.LBB0_200:
	ds_read_b128 v[148:151], v169
	ds_read_b128 v[152:155], v169 offset:1024
	ds_read_b128 v[156:159], v169 offset:2048
	ds_read_b128 v[160:163], v169 offset:3072
	ds_read_b128 v[174:177], v170
	ds_read_b128 v[178:181], v170 offset:1024
	ds_read_b128 v[182:185], v170 offset:2048
	ds_read_b128 v[186:189], v170 offset:3072
	ds_read_b128 v[190:193], v171
	ds_read_b128 v[194:197], v171 offset:1024
	ds_read_b128 v[198:201], v171 offset:2048
	ds_read_b128 v[202:205], v171 offset:3072
	ds_read_b128 v[206:209], v171 offset:4096
	ds_read_b128 v[210:213], v171 offset:5120
	ds_read_b128 v[214:217], v171 offset:6144
	ds_read_b128 v[218:221], v171 offset:7168
	s_add_u32 s26, s6, 0xfff00800
	s_addc_u32 s27, s7, -1
	s_cmp_eq_u32 s34, 60
	s_cselect_b32 s29, s17, s27
	s_cselect_b32 s28, s23, s26
	s_cselect_b32 s27, s15, s31
	s_cselect_b32 s26, s25, s30
	v_lshl_add_u64 v[222:223], s[6:7], 0, v[138:139]
	s_add_i32 m0, s41, 0xc000
	s_nop 0
	global_load_lds_dwordx4 v[222:223], off
	v_lshl_add_u64 v[222:223], s[6:7], 0, v[140:141]
	s_add_i32 m0, s41, 0xe000
	s_nop 0
	global_load_lds_dwordx4 v[222:223], off
	s_waitcnt vmcnt(8)
	s_waitcnt lgkmcnt(0)
	s_setprio 1
	s_waitcnt lgkmcnt(0)
	v_mfma_f32_16x16x32_bf16 v[124:127], v[148:151], v[190:193], v[124:127]
	v_mfma_f32_16x16x32_bf16 v[120:123], v[156:159], v[190:193], v[120:123]
	v_mfma_f32_16x16x32_bf16 v[116:119], v[148:151], v[198:201], v[116:119]
	s_barrier
	v_mfma_f32_16x16x32_bf16 v[112:115], v[156:159], v[198:201], v[112:115]
	v_mfma_f32_16x16x32_bf16 v[108:111], v[148:151], v[206:209], v[108:111]
	v_mfma_f32_16x16x32_bf16 v[104:107], v[156:159], v[206:209], v[104:107]
	v_mfma_f32_16x16x32_bf16 v[100:103], v[148:151], v[214:217], v[100:103]
	v_mfma_f32_16x16x32_bf16 v[96:99], v[156:159], v[214:217], v[96:99]
	v_mfma_f32_16x16x32_bf16 v[124:127], v[152:155], v[194:197], v[124:127]
	v_mfma_f32_16x16x32_bf16 v[120:123], v[160:163], v[194:197], v[120:123]
	v_mfma_f32_16x16x32_bf16 v[116:119], v[152:155], v[202:205], v[116:119]
	v_mfma_f32_16x16x32_bf16 v[112:115], v[160:163], v[202:205], v[112:115]
	v_mfma_f32_16x16x32_bf16 v[108:111], v[152:155], v[210:213], v[108:111]
	v_mfma_f32_16x16x32_bf16 v[104:107], v[160:163], v[210:213], v[104:107]
	v_mfma_f32_16x16x32_bf16 v[100:103], v[152:155], v[218:221], v[100:103]
	v_mfma_f32_16x16x32_bf16 v[96:99], v[160:163], v[218:221], v[96:99]
	s_setprio 0
	s_setprio 1
	v_mfma_f32_16x16x32_bf16 v[60:63], v[174:177], v[190:193], v[60:63]
	v_mfma_f32_16x16x32_bf16 v[56:59], v[182:185], v[190:193], v[56:59]
	v_mfma_f32_16x16x32_bf16 v[52:55], v[174:177], v[198:201], v[52:55]
	v_mfma_f32_16x16x32_bf16 v[48:51], v[182:185], v[198:201], v[48:51]
	v_mfma_f32_16x16x32_bf16 v[44:47], v[174:177], v[206:209], v[44:47]
	v_mfma_f32_16x16x32_bf16 v[40:43], v[182:185], v[206:209], v[40:43]
	v_mfma_f32_16x16x32_bf16 v[36:39], v[174:177], v[214:217], v[36:39]
	v_mfma_f32_16x16x32_bf16 v[32:35], v[182:185], v[214:217], v[32:35]
	v_mfma_f32_16x16x32_bf16 v[60:63], v[178:181], v[194:197], v[60:63]
	v_mfma_f32_16x16x32_bf16 v[56:59], v[186:189], v[194:197], v[56:59]
	v_mfma_f32_16x16x32_bf16 v[52:55], v[178:181], v[202:205], v[52:55]
	v_mfma_f32_16x16x32_bf16 v[48:51], v[186:189], v[202:205], v[48:51]
	v_mfma_f32_16x16x32_bf16 v[44:47], v[178:181], v[210:213], v[44:47]
	v_mfma_f32_16x16x32_bf16 v[40:43], v[186:189], v[210:213], v[40:43]
	v_mfma_f32_16x16x32_bf16 v[36:39], v[178:181], v[218:221], v[36:39]
	v_mfma_f32_16x16x32_bf16 v[32:35], v[186:189], v[218:221], v[32:35]
	s_setprio 0
	s_barrier
	ds_read_b128 v[190:193], v171 offset:16384
	ds_read_b128 v[194:197], v171 offset:17408
	ds_read_b128 v[198:201], v171 offset:18432
	ds_read_b128 v[202:205], v171 offset:19456
	ds_read_b128 v[206:209], v171 offset:20480
	ds_read_b128 v[210:213], v171 offset:21504
	ds_read_b128 v[214:217], v171 offset:22528
	ds_read_b128 v[218:221], v171 offset:23552
	s_add_i32 s35, s55, s36
	v_lshl_add_u64 v[222:223], s[26:27], 0, v[130:131]
	s_mov_b32 m0, s35
	v_lshl_add_u64 v[224:225], s[26:27], 0, v[134:135]
	global_load_lds_dwordx4 v[222:223], off
	s_add_i32 m0, s35, 0x2000
	s_add_u32 s58, s26, 0x100000
	s_addc_u32 s59, s27, 0
	s_add_i32 s35, s56, s36
	global_load_lds_dwordx4 v[224:225], off
	s_mov_b32 m0, s35
	v_lshl_add_u64 v[226:227], s[28:29], 0, v[128:129]
	global_load_lds_dwordx4 v130, s[58:59]
	s_add_i32 m0, s35, 0x2000
	v_lshl_add_u64 v[228:229], s[28:29], 0, v[132:133]
	global_load_lds_dwordx4 v134, s[58:59]
	s_mov_b32 m0, s41
	s_nop 0
	global_load_lds_dwordx4 v[226:227], off
	s_mov_b32 m0, s42
	s_nop 0
	global_load_lds_dwordx4 v[228:229], off
	s_waitcnt vmcnt(8)
	s_waitcnt lgkmcnt(0)
	s_setprio 1
	s_waitcnt lgkmcnt(0)
	v_mfma_f32_16x16x32_bf16 v[92:95], v[148:151], v[190:193], v[92:95]
	v_mfma_f32_16x16x32_bf16 v[88:91], v[156:159], v[190:193], v[88:91]
	v_mfma_f32_16x16x32_bf16 v[84:87], v[148:151], v[198:201], v[84:87]
	s_barrier
	v_mfma_f32_16x16x32_bf16 v[80:83], v[156:159], v[198:201], v[80:83]
	v_mfma_f32_16x16x32_bf16 v[76:79], v[148:151], v[206:209], v[76:79]
	v_mfma_f32_16x16x32_bf16 v[72:75], v[156:159], v[206:209], v[72:75]
	v_mfma_f32_16x16x32_bf16 v[68:71], v[148:151], v[214:217], v[68:71]
	v_mfma_f32_16x16x32_bf16 v[64:67], v[156:159], v[214:217], v[64:67]
	v_mfma_f32_16x16x32_bf16 v[92:95], v[152:155], v[194:197], v[92:95]
	v_mfma_f32_16x16x32_bf16 v[88:91], v[160:163], v[194:197], v[88:91]
	v_mfma_f32_16x16x32_bf16 v[84:87], v[152:155], v[202:205], v[84:87]
	v_mfma_f32_16x16x32_bf16 v[80:83], v[160:163], v[202:205], v[80:83]
	v_mfma_f32_16x16x32_bf16 v[76:79], v[152:155], v[210:213], v[76:79]
	v_mfma_f32_16x16x32_bf16 v[72:75], v[160:163], v[210:213], v[72:75]
	v_mfma_f32_16x16x32_bf16 v[68:71], v[152:155], v[218:221], v[68:71]
	v_mfma_f32_16x16x32_bf16 v[64:67], v[160:163], v[218:221], v[64:67]
	s_setprio 0
	s_setprio 1
	v_mfma_f32_16x16x32_bf16 v[28:31], v[174:177], v[190:193], v[28:31]
	v_mfma_f32_16x16x32_bf16 v[24:27], v[182:185], v[190:193], v[24:27]
	v_mfma_f32_16x16x32_bf16 v[20:23], v[174:177], v[198:201], v[20:23]
	v_mfma_f32_16x16x32_bf16 v[16:19], v[182:185], v[198:201], v[16:19]
	v_mfma_f32_16x16x32_bf16 v[12:15], v[174:177], v[206:209], v[12:15]
	v_mfma_f32_16x16x32_bf16 v[8:11], v[182:185], v[206:209], v[8:11]
	v_mfma_f32_16x16x32_bf16 v[4:7], v[174:177], v[214:217], v[4:7]
	v_mfma_f32_16x16x32_bf16 v[0:3], v[182:185], v[214:217], v[0:3]
	v_mfma_f32_16x16x32_bf16 v[28:31], v[178:181], v[194:197], v[28:31]
	v_mfma_f32_16x16x32_bf16 v[24:27], v[186:189], v[194:197], v[24:27]
	v_mfma_f32_16x16x32_bf16 v[20:23], v[178:181], v[202:205], v[20:23]
	v_mfma_f32_16x16x32_bf16 v[16:19], v[186:189], v[202:205], v[16:19]
	v_mfma_f32_16x16x32_bf16 v[12:15], v[178:181], v[210:213], v[12:15]
	v_mfma_f32_16x16x32_bf16 v[8:11], v[186:189], v[210:213], v[8:11]
	v_mfma_f32_16x16x32_bf16 v[4:7], v[178:181], v[218:221], v[4:7]
	v_mfma_f32_16x16x32_bf16 v[0:3], v[186:189], v[218:221], v[0:3]
	s_setprio 0
	s_barrier
	s_add_i32 s35, 0, 0x18000
	v_add_u32_e32 v136, s35, v165
	s_add_i32 s57, 0, 0x1c000
	ds_read_b128 v[148:151], v136
	ds_read_b128 v[152:155], v136 offset:1024
	ds_read_b128 v[156:159], v136 offset:2048
	ds_read_b128 v[160:163], v136 offset:3072
	v_add_u32_e32 v136, s57, v165
	ds_read_b128 v[174:177], v136
	ds_read_b128 v[178:181], v136 offset:1024
	ds_read_b128 v[182:185], v136 offset:2048
	ds_read_b128 v[186:189], v136 offset:3072
	ds_read_b128 v[190:193], v171 offset:32768
	ds_read_b128 v[194:197], v171 offset:33792
	ds_read_b128 v[198:201], v171 offset:34816
	ds_read_b128 v[202:205], v171 offset:35840
	ds_read_b128 v[206:209], v171 offset:36864
	ds_read_b128 v[210:213], v171 offset:37888
	ds_read_b128 v[214:217], v171 offset:38912
	ds_read_b128 v[218:221], v171 offset:39936
	s_add_u32 s28, s28, 0x100000
	s_addc_u32 s29, s29, 0
	s_mov_b32 m0, s43
	s_nop 0
	global_load_lds_dwordx4 v128, s[28:29]
	s_mov_b32 m0, s44
	s_nop 0
	global_load_lds_dwordx4 v132, s[28:29]
	s_waitcnt vmcnt(8)
	s_waitcnt lgkmcnt(0)
	s_setprio 1
	s_waitcnt lgkmcnt(0)
	v_mfma_f32_16x16x32_bf16 v[124:127], v[148:151], v[190:193], v[124:127]
	v_mfma_f32_16x16x32_bf16 v[120:123], v[156:159], v[190:193], v[120:123]
	v_mfma_f32_16x16x32_bf16 v[116:119], v[148:151], v[198:201], v[116:119]
	s_barrier
	v_mfma_f32_16x16x32_bf16 v[112:115], v[156:159], v[198:201], v[112:115]
	v_mfma_f32_16x16x32_bf16 v[108:111], v[148:151], v[206:209], v[108:111]
	v_mfma_f32_16x16x32_bf16 v[104:107], v[156:159], v[206:209], v[104:107]
	v_mfma_f32_16x16x32_bf16 v[100:103], v[148:151], v[214:217], v[100:103]
	v_mfma_f32_16x16x32_bf16 v[96:99], v[156:159], v[214:217], v[96:99]
	v_mfma_f32_16x16x32_bf16 v[124:127], v[152:155], v[194:197], v[124:127]
	v_mfma_f32_16x16x32_bf16 v[120:123], v[160:163], v[194:197], v[120:123]
	v_mfma_f32_16x16x32_bf16 v[116:119], v[152:155], v[202:205], v[116:119]
	v_mfma_f32_16x16x32_bf16 v[112:115], v[160:163], v[202:205], v[112:115]
	v_mfma_f32_16x16x32_bf16 v[108:111], v[152:155], v[210:213], v[108:111]
	v_mfma_f32_16x16x32_bf16 v[104:107], v[160:163], v[210:213], v[104:107]
	v_mfma_f32_16x16x32_bf16 v[100:103], v[152:155], v[218:221], v[100:103]
	v_mfma_f32_16x16x32_bf16 v[96:99], v[160:163], v[218:221], v[96:99]
	s_setprio 0
	s_setprio 1
	v_mfma_f32_16x16x32_bf16 v[60:63], v[174:177], v[190:193], v[60:63]
	v_mfma_f32_16x16x32_bf16 v[56:59], v[182:185], v[190:193], v[56:59]
	v_mfma_f32_16x16x32_bf16 v[52:55], v[174:177], v[198:201], v[52:55]
	v_mfma_f32_16x16x32_bf16 v[48:51], v[182:185], v[198:201], v[48:51]
	v_mfma_f32_16x16x32_bf16 v[44:47], v[174:177], v[206:209], v[44:47]
	v_mfma_f32_16x16x32_bf16 v[40:43], v[182:185], v[206:209], v[40:43]
	v_mfma_f32_16x16x32_bf16 v[36:39], v[174:177], v[214:217], v[36:39]
	v_mfma_f32_16x16x32_bf16 v[32:35], v[182:185], v[214:217], v[32:35]
	v_mfma_f32_16x16x32_bf16 v[60:63], v[178:181], v[194:197], v[60:63]
	v_mfma_f32_16x16x32_bf16 v[56:59], v[186:189], v[194:197], v[56:59]
	v_mfma_f32_16x16x32_bf16 v[52:55], v[178:181], v[202:205], v[52:55]
	v_mfma_f32_16x16x32_bf16 v[48:51], v[186:189], v[202:205], v[48:51]
	v_mfma_f32_16x16x32_bf16 v[44:47], v[178:181], v[210:213], v[44:47]
	v_mfma_f32_16x16x32_bf16 v[40:43], v[186:189], v[210:213], v[40:43]
	v_mfma_f32_16x16x32_bf16 v[36:39], v[178:181], v[218:221], v[36:39]
	v_mfma_f32_16x16x32_bf16 v[32:35], v[186:189], v[218:221], v[32:35]
	s_setprio 0
	s_barrier
	ds_read_b128 v[190:193], v171 offset:49152
	ds_read_b128 v[194:197], v171 offset:50176
	ds_read_b128 v[198:201], v171 offset:51200
	ds_read_b128 v[202:205], v171 offset:52224
	ds_read_b128 v[206:209], v171 offset:53248
	ds_read_b128 v[210:213], v171 offset:54272
	ds_read_b128 v[214:217], v171 offset:55296
	ds_read_b128 v[218:221], v171 offset:56320
	s_add_i32 s28, s35, s36
	v_lshl_add_u64 v[222:223], v[222:223], 0, s[12:13]
	s_mov_b32 m0, s28
	s_nop 0
	global_load_lds_dwordx4 v[222:223], off
	s_add_i32 m0, s28, 0x2000
	s_add_u32 s26, s26, 0x100800
	v_lshl_add_u64 v[224:225], v[224:225], 0, s[12:13]
	s_addc_u32 s27, s27, 0
	s_add_i32 s28, s57, s36
	global_load_lds_dwordx4 v[224:225], off
	s_mov_b32 m0, s28
	s_nop 0
	global_load_lds_dwordx4 v130, s[26:27]
	s_add_i32 m0, s28, 0x2000
	s_nop 0
	global_load_lds_dwordx4 v134, s[26:27]
	v_lshl_add_u64 v[226:227], v[226:227], 0, s[12:13]
	s_mov_b32 m0, s49
	s_nop 0
	global_load_lds_dwordx4 v[226:227], off
	v_lshl_add_u64 v[228:229], v[228:229], 0, s[12:13]
	s_mov_b32 m0, s50
	s_nop 0
	global_load_lds_dwordx4 v[228:229], off
	s_waitcnt vmcnt(8)
	s_waitcnt lgkmcnt(0)
	s_setprio 1
	s_waitcnt lgkmcnt(0)
	v_mfma_f32_16x16x32_bf16 v[92:95], v[148:151], v[190:193], v[92:95]
	v_mfma_f32_16x16x32_bf16 v[88:91], v[156:159], v[190:193], v[88:91]
	v_mfma_f32_16x16x32_bf16 v[84:87], v[148:151], v[198:201], v[84:87]
	s_barrier
	v_mfma_f32_16x16x32_bf16 v[80:83], v[156:159], v[198:201], v[80:83]
	v_mfma_f32_16x16x32_bf16 v[76:79], v[148:151], v[206:209], v[76:79]
	v_mfma_f32_16x16x32_bf16 v[72:75], v[156:159], v[206:209], v[72:75]
	v_mfma_f32_16x16x32_bf16 v[68:71], v[148:151], v[214:217], v[68:71]
	v_mfma_f32_16x16x32_bf16 v[64:67], v[156:159], v[214:217], v[64:67]
	v_mfma_f32_16x16x32_bf16 v[92:95], v[152:155], v[194:197], v[92:95]
	v_mfma_f32_16x16x32_bf16 v[88:91], v[160:163], v[194:197], v[88:91]
	v_mfma_f32_16x16x32_bf16 v[84:87], v[152:155], v[202:205], v[84:87]
	v_mfma_f32_16x16x32_bf16 v[80:83], v[160:163], v[202:205], v[80:83]
	v_mfma_f32_16x16x32_bf16 v[76:79], v[152:155], v[210:213], v[76:79]
	v_mfma_f32_16x16x32_bf16 v[72:75], v[160:163], v[210:213], v[72:75]
	v_mfma_f32_16x16x32_bf16 v[68:71], v[152:155], v[218:221], v[68:71]
	v_mfma_f32_16x16x32_bf16 v[64:67], v[160:163], v[218:221], v[64:67]
	s_setprio 0
	s_setprio 1
	v_mfma_f32_16x16x32_bf16 v[28:31], v[174:177], v[190:193], v[28:31]
	v_mfma_f32_16x16x32_bf16 v[24:27], v[182:185], v[190:193], v[24:27]
	v_mfma_f32_16x16x32_bf16 v[20:23], v[174:177], v[198:201], v[20:23]
	v_mfma_f32_16x16x32_bf16 v[16:19], v[182:185], v[198:201], v[16:19]
	v_mfma_f32_16x16x32_bf16 v[12:15], v[174:177], v[206:209], v[12:15]
	v_mfma_f32_16x16x32_bf16 v[8:11], v[182:185], v[206:209], v[8:11]
	v_mfma_f32_16x16x32_bf16 v[4:7], v[174:177], v[214:217], v[4:7]
	v_mfma_f32_16x16x32_bf16 v[0:3], v[182:185], v[214:217], v[0:3]
	v_mfma_f32_16x16x32_bf16 v[28:31], v[178:181], v[194:197], v[28:31]
	v_mfma_f32_16x16x32_bf16 v[24:27], v[186:189], v[194:197], v[24:27]
	v_mfma_f32_16x16x32_bf16 v[20:23], v[178:181], v[202:205], v[20:23]
	v_mfma_f32_16x16x32_bf16 v[16:19], v[186:189], v[202:205], v[16:19]
	v_mfma_f32_16x16x32_bf16 v[12:15], v[178:181], v[210:213], v[12:15]
	v_mfma_f32_16x16x32_bf16 v[8:11], v[186:189], v[210:213], v[8:11]
	v_mfma_f32_16x16x32_bf16 v[4:7], v[178:181], v[218:221], v[4:7]
	v_mfma_f32_16x16x32_bf16 v[0:3], v[186:189], v[218:221], v[0:3]
	s_setprio 0
	s_barrier
	s_add_i32 s34, s34, 2
	s_add_u32 s6, s6, 0x1000
	s_addc_u32 s7, s7, 0
	s_add_u32 s30, s30, 0x1000
	s_addc_u32 s31, s31, 0
	s_cmp_gt_u32 s34, 61
	s_cbranch_scc0 .LBB0_200
	s_and_b64 vcc, exec, s[0:1]
	s_cbranch_vccz .LBB0_203
	s_barrier

.LBB0_333:
	ds_read_b128 v[144:147], v152
	ds_read_b128 v[156:159], v152 offset:1024
	ds_read_b128 v[160:163], v152 offset:2048
	ds_read_b128 v[164:167], v152 offset:3072
	ds_read_b128 v[168:171], v153
	ds_read_b128 v[172:175], v153 offset:1024
	ds_read_b128 v[176:179], v153 offset:2048
	ds_read_b128 v[180:183], v153 offset:3072
	ds_read_b128 v[184:187], v154
	ds_read_b128 v[188:191], v154 offset:1024
	ds_read_b128 v[192:195], v154 offset:2048
	ds_read_b128 v[196:199], v154 offset:3072
	ds_read_b128 v[200:203], v154 offset:4096
	ds_read_b128 v[204:207], v154 offset:5120
	ds_read_b128 v[208:211], v154 offset:6144
	ds_read_b128 v[212:215], v154 offset:7168
	s_add_u32 s28, s24, 0x100
	s_addc_u32 s29, s25, 0
	s_cmp_eq_u32 s56, 60
	s_cselect_b32 s35, s13, s29
	s_cselect_b32 s34, s52, s28
	s_cselect_b32 s31, s11, s55
	s_cselect_b32 s30, s53, s54
	v_lshl_add_u64 v[216:217], s[24:25], 0, v[136:137]
	s_add_i32 m0, s21, 0xc000
	s_nop 0
	global_load_lds_dwordx4 v[216:217], off
	v_lshl_add_u64 v[216:217], s[24:25], 0, v[138:139]
	s_add_i32 m0, s21, 0xe000
	s_nop 0
	global_load_lds_dwordx4 v[216:217], off
	s_waitcnt vmcnt(8)
	s_waitcnt lgkmcnt(0)
	s_setprio 1
	s_waitcnt lgkmcnt(0)
	v_mfma_f32_16x16x32_bf16 v[124:127], v[144:147], v[184:187], v[124:127]
	v_mfma_f32_16x16x32_bf16 v[120:123], v[160:163], v[184:187], v[120:123]
	v_mfma_f32_16x16x32_bf16 v[116:119], v[144:147], v[192:195], v[116:119]
	s_barrier
	v_mfma_f32_16x16x32_bf16 v[108:111], v[160:163], v[192:195], v[108:111]
	v_mfma_f32_16x16x32_bf16 v[100:103], v[144:147], v[200:203], v[100:103]
	v_mfma_f32_16x16x32_bf16 v[92:95], v[160:163], v[200:203], v[92:95]
	v_mfma_f32_16x16x32_bf16 v[84:87], v[144:147], v[208:211], v[84:87]
	v_mfma_f32_16x16x32_bf16 v[76:79], v[160:163], v[208:211], v[76:79]
	v_mfma_f32_16x16x32_bf16 v[124:127], v[156:159], v[188:191], v[124:127]
	v_mfma_f32_16x16x32_bf16 v[120:123], v[164:167], v[188:191], v[120:123]
	v_mfma_f32_16x16x32_bf16 v[116:119], v[156:159], v[196:199], v[116:119]
	v_mfma_f32_16x16x32_bf16 v[108:111], v[164:167], v[196:199], v[108:111]
	v_mfma_f32_16x16x32_bf16 v[100:103], v[156:159], v[204:207], v[100:103]
	v_mfma_f32_16x16x32_bf16 v[92:95], v[164:167], v[204:207], v[92:95]
	v_mfma_f32_16x16x32_bf16 v[84:87], v[156:159], v[212:215], v[84:87]
	v_mfma_f32_16x16x32_bf16 v[76:79], v[164:167], v[212:215], v[76:79]
	s_setprio 0
	s_setprio 1
	v_mfma_f32_16x16x32_bf16 v[112:115], v[168:171], v[184:187], v[112:115]
	v_mfma_f32_16x16x32_bf16 v[104:107], v[176:179], v[184:187], v[104:107]
	v_mfma_f32_16x16x32_bf16 v[96:99], v[168:171], v[192:195], v[96:99]
	v_mfma_f32_16x16x32_bf16 v[88:91], v[176:179], v[192:195], v[88:91]
	v_mfma_f32_16x16x32_bf16 v[80:83], v[168:171], v[200:203], v[80:83]
	v_mfma_f32_16x16x32_bf16 v[72:75], v[176:179], v[200:203], v[72:75]
	v_mfma_f32_16x16x32_bf16 v[68:71], v[168:171], v[208:211], v[68:71]
	v_mfma_f32_16x16x32_bf16 v[64:67], v[176:179], v[208:211], v[64:67]
	v_mfma_f32_16x16x32_bf16 v[112:115], v[172:175], v[188:191], v[112:115]
	v_mfma_f32_16x16x32_bf16 v[104:107], v[180:183], v[188:191], v[104:107]
	v_mfma_f32_16x16x32_bf16 v[96:99], v[172:175], v[196:199], v[96:99]
	v_mfma_f32_16x16x32_bf16 v[88:91], v[180:183], v[196:199], v[88:91]
	v_mfma_f32_16x16x32_bf16 v[80:83], v[172:175], v[204:207], v[80:83]
	v_mfma_f32_16x16x32_bf16 v[72:75], v[180:183], v[204:207], v[72:75]
	v_mfma_f32_16x16x32_bf16 v[68:71], v[172:175], v[212:215], v[68:71]
	v_mfma_f32_16x16x32_bf16 v[64:67], v[180:183], v[212:215], v[64:67]
	s_setprio 0
	s_barrier
	ds_read_b128 v[184:187], v154 offset:16384
	ds_read_b128 v[188:191], v154 offset:17408
	ds_read_b128 v[192:195], v154 offset:18432
	ds_read_b128 v[196:199], v154 offset:19456
	ds_read_b128 v[200:203], v154 offset:20480
	ds_read_b128 v[204:207], v154 offset:21504
	ds_read_b128 v[208:211], v154 offset:22528
	ds_read_b128 v[212:215], v154 offset:23552
	s_add_i32 s24, s49, s41
	v_lshl_add_u64 v[216:217], s[30:31], 0, v[130:131]
	s_mov_b32 m0, s24
	v_lshl_add_u64 v[218:219], s[30:31], 0, v[134:135]
	global_load_lds_dwordx4 v[216:217], off
	s_add_i32 m0, s24, 0x2000
	s_add_u32 s24, s30, 0x100000
	s_addc_u32 s25, s31, 0
	s_add_i32 s57, s50, s41
	global_load_lds_dwordx4 v[218:219], off
	s_mov_b32 m0, s57
	v_lshl_add_u64 v[220:221], s[34:35], 0, v[128:129]
	global_load_lds_dwordx4 v130, s[24:25]
	s_add_i32 m0, s57, 0x2000
	v_lshl_add_u64 v[222:223], s[34:35], 0, v[132:133]
	global_load_lds_dwordx4 v134, s[24:25]
	s_mov_b32 m0, s21
	s_nop 0
	global_load_lds_dwordx4 v[220:221], off
	s_mov_b32 m0, s42
	s_nop 0
	global_load_lds_dwordx4 v[222:223], off
	s_waitcnt vmcnt(8)
	s_waitcnt lgkmcnt(0)
	s_setprio 1
	s_waitcnt lgkmcnt(0)
	v_mfma_f32_16x16x32_bf16 v[60:63], v[144:147], v[184:187], v[60:63]
	v_mfma_f32_16x16x32_bf16 v[56:59], v[160:163], v[184:187], v[56:59]
	v_mfma_f32_16x16x32_bf16 v[52:55], v[144:147], v[192:195], v[52:55]
	s_barrier
	v_mfma_f32_16x16x32_bf16 v[44:47], v[160:163], v[192:195], v[44:47]
	v_mfma_f32_16x16x32_bf16 v[36:39], v[144:147], v[200:203], v[36:39]
	v_mfma_f32_16x16x32_bf16 v[28:31], v[160:163], v[200:203], v[28:31]
	v_mfma_f32_16x16x32_bf16 v[20:23], v[144:147], v[208:211], v[20:23]
	v_mfma_f32_16x16x32_bf16 v[12:15], v[160:163], v[208:211], v[12:15]
	v_mfma_f32_16x16x32_bf16 v[60:63], v[156:159], v[188:191], v[60:63]
	v_mfma_f32_16x16x32_bf16 v[56:59], v[164:167], v[188:191], v[56:59]
	v_mfma_f32_16x16x32_bf16 v[52:55], v[156:159], v[196:199], v[52:55]
	v_mfma_f32_16x16x32_bf16 v[44:47], v[164:167], v[196:199], v[44:47]
	v_mfma_f32_16x16x32_bf16 v[36:39], v[156:159], v[204:207], v[36:39]
	v_mfma_f32_16x16x32_bf16 v[28:31], v[164:167], v[204:207], v[28:31]
	v_mfma_f32_16x16x32_bf16 v[20:23], v[156:159], v[212:215], v[20:23]
	v_mfma_f32_16x16x32_bf16 v[12:15], v[164:167], v[212:215], v[12:15]
	s_setprio 0
	s_setprio 1
	v_mfma_f32_16x16x32_bf16 v[48:51], v[168:171], v[184:187], v[48:51]
	v_mfma_f32_16x16x32_bf16 v[40:43], v[176:179], v[184:187], v[40:43]
	v_mfma_f32_16x16x32_bf16 v[32:35], v[168:171], v[192:195], v[32:35]
	v_mfma_f32_16x16x32_bf16 v[24:27], v[176:179], v[192:195], v[24:27]
	v_mfma_f32_16x16x32_bf16 v[16:19], v[168:171], v[200:203], v[16:19]
	v_mfma_f32_16x16x32_bf16 v[8:11], v[176:179], v[200:203], v[8:11]
	v_mfma_f32_16x16x32_bf16 v[4:7], v[168:171], v[208:211], v[4:7]
	v_mfma_f32_16x16x32_bf16 v[0:3], v[176:179], v[208:211], v[0:3]
	v_mfma_f32_16x16x32_bf16 v[48:51], v[172:175], v[188:191], v[48:51]
	v_mfma_f32_16x16x32_bf16 v[40:43], v[180:183], v[188:191], v[40:43]
	v_mfma_f32_16x16x32_bf16 v[32:35], v[172:175], v[196:199], v[32:35]
	v_mfma_f32_16x16x32_bf16 v[24:27], v[180:183], v[196:199], v[24:27]
	v_mfma_f32_16x16x32_bf16 v[16:19], v[172:175], v[204:207], v[16:19]
	v_mfma_f32_16x16x32_bf16 v[8:11], v[180:183], v[204:207], v[8:11]
	v_mfma_f32_16x16x32_bf16 v[4:7], v[172:175], v[212:215], v[4:7]
	v_mfma_f32_16x16x32_bf16 v[0:3], v[180:183], v[212:215], v[0:3]
	s_setprio 0
	s_barrier
	s_add_i32 s57, 0, 0x18000
	v_add_u32_e32 v155, s57, v149
	s_add_i32 s58, 0, 0x1c000
	ds_read_b128 v[144:147], v155
	ds_read_b128 v[156:159], v155 offset:1024
	ds_read_b128 v[160:163], v155 offset:2048
	ds_read_b128 v[164:167], v155 offset:3072
	v_add_u32_e32 v155, s58, v149
	ds_read_b128 v[168:171], v155
	ds_read_b128 v[172:175], v155 offset:1024
	ds_read_b128 v[176:179], v155 offset:2048
	ds_read_b128 v[180:183], v155 offset:3072
	ds_read_b128 v[184:187], v154 offset:32768
	ds_read_b128 v[188:191], v154 offset:33792
	ds_read_b128 v[192:195], v154 offset:34816
	ds_read_b128 v[196:199], v154 offset:35840
	ds_read_b128 v[200:203], v154 offset:36864
	ds_read_b128 v[204:207], v154 offset:37888
	ds_read_b128 v[208:211], v154 offset:38912
	ds_read_b128 v[212:215], v154 offset:39936
	s_add_u32 s24, s34, 0x100000
	s_addc_u32 s25, s35, 0
	s_mov_b32 m0, s43
	s_nop 0
	global_load_lds_dwordx4 v128, s[24:25]
	s_mov_b32 m0, s44
	s_nop 0
	global_load_lds_dwordx4 v132, s[24:25]
	s_waitcnt vmcnt(8)
	s_waitcnt lgkmcnt(0)
	s_setprio 1
	s_waitcnt lgkmcnt(0)
	v_mfma_f32_16x16x32_bf16 v[124:127], v[144:147], v[184:187], v[124:127]
	v_mfma_f32_16x16x32_bf16 v[120:123], v[160:163], v[184:187], v[120:123]
	v_mfma_f32_16x16x32_bf16 v[116:119], v[144:147], v[192:195], v[116:119]
	s_barrier
	v_mfma_f32_16x16x32_bf16 v[108:111], v[160:163], v[192:195], v[108:111]
	v_mfma_f32_16x16x32_bf16 v[100:103], v[144:147], v[200:203], v[100:103]
	v_mfma_f32_16x16x32_bf16 v[92:95], v[160:163], v[200:203], v[92:95]
	v_mfma_f32_16x16x32_bf16 v[84:87], v[144:147], v[208:211], v[84:87]
	v_mfma_f32_16x16x32_bf16 v[76:79], v[160:163], v[208:211], v[76:79]
	v_mfma_f32_16x16x32_bf16 v[124:127], v[156:159], v[188:191], v[124:127]
	v_mfma_f32_16x16x32_bf16 v[120:123], v[164:167], v[188:191], v[120:123]
	v_mfma_f32_16x16x32_bf16 v[116:119], v[156:159], v[196:199], v[116:119]
	v_mfma_f32_16x16x32_bf16 v[108:111], v[164:167], v[196:199], v[108:111]
	v_mfma_f32_16x16x32_bf16 v[100:103], v[156:159], v[204:207], v[100:103]
	v_mfma_f32_16x16x32_bf16 v[92:95], v[164:167], v[204:207], v[92:95]
	v_mfma_f32_16x16x32_bf16 v[84:87], v[156:159], v[212:215], v[84:87]
	v_mfma_f32_16x16x32_bf16 v[76:79], v[164:167], v[212:215], v[76:79]
	s_setprio 0
	s_setprio 1
	v_mfma_f32_16x16x32_bf16 v[112:115], v[168:171], v[184:187], v[112:115]
	v_mfma_f32_16x16x32_bf16 v[104:107], v[176:179], v[184:187], v[104:107]
	v_mfma_f32_16x16x32_bf16 v[96:99], v[168:171], v[192:195], v[96:99]
	v_mfma_f32_16x16x32_bf16 v[88:91], v[176:179], v[192:195], v[88:91]
	v_mfma_f32_16x16x32_bf16 v[80:83], v[168:171], v[200:203], v[80:83]
	v_mfma_f32_16x16x32_bf16 v[72:75], v[176:179], v[200:203], v[72:75]
	v_mfma_f32_16x16x32_bf16 v[68:71], v[168:171], v[208:211], v[68:71]
	v_mfma_f32_16x16x32_bf16 v[64:67], v[176:179], v[208:211], v[64:67]
	v_mfma_f32_16x16x32_bf16 v[112:115], v[172:175], v[188:191], v[112:115]
	v_mfma_f32_16x16x32_bf16 v[104:107], v[180:183], v[188:191], v[104:107]
	v_mfma_f32_16x16x32_bf16 v[96:99], v[172:175], v[196:199], v[96:99]
	v_mfma_f32_16x16x32_bf16 v[88:91], v[180:183], v[196:199], v[88:91]
	v_mfma_f32_16x16x32_bf16 v[80:83], v[172:175], v[204:207], v[80:83]
	v_mfma_f32_16x16x32_bf16 v[72:75], v[180:183], v[204:207], v[72:75]
	v_mfma_f32_16x16x32_bf16 v[68:71], v[172:175], v[212:215], v[68:71]
	v_mfma_f32_16x16x32_bf16 v[64:67], v[180:183], v[212:215], v[64:67]
	s_setprio 0
	s_barrier
	ds_read_b128 v[184:187], v154 offset:49152
	ds_read_b128 v[188:191], v154 offset:50176
	ds_read_b128 v[192:195], v154 offset:51200
	ds_read_b128 v[196:199], v154 offset:52224
	ds_read_b128 v[200:203], v154 offset:53248
	ds_read_b128 v[204:207], v154 offset:54272
	ds_read_b128 v[208:211], v154 offset:55296
	ds_read_b128 v[212:215], v154 offset:56320
	s_add_i32 s24, s57, s41
	v_lshl_add_u64 v[216:217], v[216:217], 0, s[8:9]
	s_mov_b32 m0, s24
	s_nop 0
	global_load_lds_dwordx4 v[216:217], off
	s_add_i32 m0, s24, 0x2000
	s_add_u32 s24, s30, 0x100080
	v_lshl_add_u64 v[218:219], v[218:219], 0, s[8:9]
	s_addc_u32 s25, s31, 0
	s_add_i32 s30, s58, s41
	global_load_lds_dwordx4 v[218:219], off
	s_mov_b32 m0, s30
	s_nop 0
	global_load_lds_dwordx4 v130, s[24:25]
	s_add_i32 m0, s30, 0x2000
	s_nop 0
	global_load_lds_dwordx4 v134, s[24:25]
	v_lshl_add_u64 v[220:221], v[220:221], 0, s[8:9]
	s_mov_b32 m0, s46
	s_nop 0
	global_load_lds_dwordx4 v[220:221], off
	v_lshl_add_u64 v[222:223], v[222:223], 0, s[8:9]
	s_mov_b32 m0, s47
	s_nop 0
	global_load_lds_dwordx4 v[222:223], off
	s_waitcnt vmcnt(8)
	s_waitcnt lgkmcnt(0)
	s_setprio 1
	s_waitcnt lgkmcnt(0)
	v_mfma_f32_16x16x32_bf16 v[60:63], v[144:147], v[184:187], v[60:63]
	v_mfma_f32_16x16x32_bf16 v[56:59], v[160:163], v[184:187], v[56:59]
	v_mfma_f32_16x16x32_bf16 v[52:55], v[144:147], v[192:195], v[52:55]
	s_barrier
	v_mfma_f32_16x16x32_bf16 v[44:47], v[160:163], v[192:195], v[44:47]
	v_mfma_f32_16x16x32_bf16 v[36:39], v[144:147], v[200:203], v[36:39]
	v_mfma_f32_16x16x32_bf16 v[28:31], v[160:163], v[200:203], v[28:31]
	v_mfma_f32_16x16x32_bf16 v[20:23], v[144:147], v[208:211], v[20:23]
	v_mfma_f32_16x16x32_bf16 v[12:15], v[160:163], v[208:211], v[12:15]
	v_mfma_f32_16x16x32_bf16 v[60:63], v[156:159], v[188:191], v[60:63]
	v_mfma_f32_16x16x32_bf16 v[56:59], v[164:167], v[188:191], v[56:59]
	v_mfma_f32_16x16x32_bf16 v[52:55], v[156:159], v[196:199], v[52:55]
	v_mfma_f32_16x16x32_bf16 v[44:47], v[164:167], v[196:199], v[44:47]
	v_mfma_f32_16x16x32_bf16 v[36:39], v[156:159], v[204:207], v[36:39]
	v_mfma_f32_16x16x32_bf16 v[28:31], v[164:167], v[204:207], v[28:31]
	v_mfma_f32_16x16x32_bf16 v[20:23], v[156:159], v[212:215], v[20:23]
	v_mfma_f32_16x16x32_bf16 v[12:15], v[164:167], v[212:215], v[12:15]
	s_setprio 0
	s_setprio 1
	v_mfma_f32_16x16x32_bf16 v[48:51], v[168:171], v[184:187], v[48:51]
	v_mfma_f32_16x16x32_bf16 v[40:43], v[176:179], v[184:187], v[40:43]
	v_mfma_f32_16x16x32_bf16 v[32:35], v[168:171], v[192:195], v[32:35]
	v_mfma_f32_16x16x32_bf16 v[24:27], v[176:179], v[192:195], v[24:27]
	v_mfma_f32_16x16x32_bf16 v[16:19], v[168:171], v[200:203], v[16:19]
	v_mfma_f32_16x16x32_bf16 v[8:11], v[176:179], v[200:203], v[8:11]
	v_mfma_f32_16x16x32_bf16 v[4:7], v[168:171], v[208:211], v[4:7]
	v_mfma_f32_16x16x32_bf16 v[0:3], v[176:179], v[208:211], v[0:3]
	v_mfma_f32_16x16x32_bf16 v[48:51], v[172:175], v[188:191], v[48:51]
	v_mfma_f32_16x16x32_bf16 v[40:43], v[180:183], v[188:191], v[40:43]
	v_mfma_f32_16x16x32_bf16 v[32:35], v[172:175], v[196:199], v[32:35]
	v_mfma_f32_16x16x32_bf16 v[24:27], v[180:183], v[196:199], v[24:27]
	v_mfma_f32_16x16x32_bf16 v[16:19], v[172:175], v[204:207], v[16:19]
	v_mfma_f32_16x16x32_bf16 v[8:11], v[180:183], v[204:207], v[8:11]
	v_mfma_f32_16x16x32_bf16 v[4:7], v[172:175], v[212:215], v[4:7]
	v_mfma_f32_16x16x32_bf16 v[0:3], v[180:183], v[212:215], v[0:3]
	s_setprio 0
	s_barrier
	s_add_i32 s56, s56, 2
	s_add_u32 s54, s54, 0x100
	s_addc_u32 s55, s55, 0
	s_cmp_gt_u32 s56, 61
	s_mov_b64 s[24:25], s[28:29]
	s_cbranch_scc0 .LBB0_333
	s_and_b64 vcc, exec, s[0:1]
	s_cbranch_vccz .LBB0_336
	s_barrier

.LBB0_1202:
	ds_read_b128 v[128:131], v176
	ds_read_b128 v[132:135], v176 offset:1024
	ds_read_b128 v[136:139], v176 offset:2048
	ds_read_b128 v[140:143], v176 offset:3072
	ds_read_b128 v[144:147], v177
	ds_read_b128 v[148:151], v177 offset:1024
	ds_read_b128 v[180:183], v177 offset:2048
	ds_read_b128 v[184:187], v177 offset:3072
	ds_read_b128 v[188:191], v178
	ds_read_b128 v[192:195], v178 offset:1024
	ds_read_b128 v[196:199], v178 offset:2048
	ds_read_b128 v[200:203], v178 offset:3072
	ds_read_b128 v[204:207], v178 offset:4096
	ds_read_b128 v[208:211], v178 offset:5120
	ds_read_b128 v[212:215], v178 offset:6144
	ds_read_b128 v[216:219], v178 offset:7168
	s_add_u32 s30, s28, 0xfff00080
	s_addc_u32 s31, s29, -1
	s_cmp_eq_u32 s40, 60
	s_cselect_b32 s35, s23, s31
	s_cselect_b32 s34, s36, s30
	s_cselect_b32 s31, s21, s39
	s_cselect_b32 s30, s37, s38
	v_lshl_add_u64 v[172:173], s[28:29], 0, v[164:165]
	s_add_i32 m0, s7, 0xc000
	s_nop 0
	global_load_lds_dwordx4 v[172:173], off
	v_lshl_add_u64 v[172:173], s[28:29], 0, v[166:167]
	s_add_i32 m0, s7, 0xe000
	s_nop 0
	global_load_lds_dwordx4 v[172:173], off
	s_waitcnt vmcnt(8)
	s_waitcnt lgkmcnt(0)
	s_setprio 1
	s_waitcnt lgkmcnt(0)
	v_mfma_f32_16x16x32_bf16 v[124:127], v[128:131], v[188:191], v[124:127]
	v_mfma_f32_16x16x32_bf16 v[120:123], v[136:139], v[188:191], v[120:123]
	v_mfma_f32_16x16x32_bf16 v[108:111], v[128:131], v[196:199], v[108:111]
	s_barrier
	v_mfma_f32_16x16x32_bf16 v[104:107], v[136:139], v[196:199], v[104:107]
	v_mfma_f32_16x16x32_bf16 v[92:95], v[128:131], v[204:207], v[92:95]
	v_mfma_f32_16x16x32_bf16 v[88:91], v[136:139], v[204:207], v[88:91]
	v_mfma_f32_16x16x32_bf16 v[76:79], v[128:131], v[212:215], v[76:79]
	v_mfma_f32_16x16x32_bf16 v[72:75], v[136:139], v[212:215], v[72:75]
	v_mfma_f32_16x16x32_bf16 v[124:127], v[132:135], v[192:195], v[124:127]
	v_mfma_f32_16x16x32_bf16 v[120:123], v[140:143], v[192:195], v[120:123]
	v_mfma_f32_16x16x32_bf16 v[108:111], v[132:135], v[200:203], v[108:111]
	v_mfma_f32_16x16x32_bf16 v[104:107], v[140:143], v[200:203], v[104:107]
	v_mfma_f32_16x16x32_bf16 v[92:95], v[132:135], v[208:211], v[92:95]
	v_mfma_f32_16x16x32_bf16 v[88:91], v[140:143], v[208:211], v[88:91]
	v_mfma_f32_16x16x32_bf16 v[76:79], v[132:135], v[216:219], v[76:79]
	v_mfma_f32_16x16x32_bf16 v[72:75], v[140:143], v[216:219], v[72:75]
	s_setprio 0
	s_setprio 1
	v_mfma_f32_16x16x32_bf16 v[116:119], v[144:147], v[188:191], v[116:119]
	v_mfma_f32_16x16x32_bf16 v[112:115], v[180:183], v[188:191], v[112:115]
	v_mfma_f32_16x16x32_bf16 v[100:103], v[144:147], v[196:199], v[100:103]
	v_mfma_f32_16x16x32_bf16 v[96:99], v[180:183], v[196:199], v[96:99]
	v_mfma_f32_16x16x32_bf16 v[84:87], v[144:147], v[204:207], v[84:87]
	v_mfma_f32_16x16x32_bf16 v[80:83], v[180:183], v[204:207], v[80:83]
	v_mfma_f32_16x16x32_bf16 v[68:71], v[144:147], v[212:215], v[68:71]
	v_mfma_f32_16x16x32_bf16 v[64:67], v[180:183], v[212:215], v[64:67]
	v_mfma_f32_16x16x32_bf16 v[116:119], v[148:151], v[192:195], v[116:119]
	v_mfma_f32_16x16x32_bf16 v[112:115], v[184:187], v[192:195], v[112:115]
	v_mfma_f32_16x16x32_bf16 v[100:103], v[148:151], v[200:203], v[100:103]
	v_mfma_f32_16x16x32_bf16 v[96:99], v[184:187], v[200:203], v[96:99]
	v_mfma_f32_16x16x32_bf16 v[84:87], v[148:151], v[208:211], v[84:87]
	v_mfma_f32_16x16x32_bf16 v[80:83], v[184:187], v[208:211], v[80:83]
	v_mfma_f32_16x16x32_bf16 v[68:71], v[148:151], v[216:219], v[68:71]
	v_mfma_f32_16x16x32_bf16 v[64:67], v[184:187], v[216:219], v[64:67]
	s_setprio 0
	s_barrier
	ds_read_b128 v[188:191], v178 offset:16384
	ds_read_b128 v[192:195], v178 offset:17408
	ds_read_b128 v[196:199], v178 offset:18432
	ds_read_b128 v[200:203], v178 offset:19456
	ds_read_b128 v[204:207], v178 offset:20480
	ds_read_b128 v[208:211], v178 offset:21504
	ds_read_b128 v[212:215], v178 offset:22528
	ds_read_b128 v[216:219], v178 offset:23552
	s_add_i32 s41, s68, s33
	v_lshl_add_u64 v[172:173], s[30:31], 0, v[154:155]
	s_mov_b32 m0, s41
	v_lshl_add_u64 v[220:221], s[30:31], 0, v[158:159]
	global_load_lds_dwordx4 v[172:173], off
	s_add_i32 m0, s41, 0x2000
	s_add_u32 s42, s30, 0x100000
	s_addc_u32 s43, s31, 0
	s_add_i32 s41, s69, s33
	global_load_lds_dwordx4 v[220:221], off
	s_mov_b32 m0, s41
	v_lshl_add_u64 v[222:223], s[34:35], 0, v[152:153]
	global_load_lds_dwordx4 v154, s[42:43]
	s_add_i32 m0, s41, 0x2000
	v_lshl_add_u64 v[224:225], s[34:35], 0, v[156:157]
	global_load_lds_dwordx4 v158, s[42:43]
	s_mov_b32 m0, s7
	s_nop 0
	global_load_lds_dwordx4 v[222:223], off
	s_mov_b32 m0, s59
	s_nop 0
	global_load_lds_dwordx4 v[224:225], off
	s_waitcnt vmcnt(8)
	s_waitcnt lgkmcnt(0)
	s_setprio 1
	s_waitcnt lgkmcnt(0)
	v_mfma_f32_16x16x32_bf16 v[60:63], v[128:131], v[188:191], v[60:63]
	v_mfma_f32_16x16x32_bf16 v[56:59], v[136:139], v[188:191], v[56:59]
	v_mfma_f32_16x16x32_bf16 v[44:47], v[128:131], v[196:199], v[44:47]
	s_barrier
	v_mfma_f32_16x16x32_bf16 v[40:43], v[136:139], v[196:199], v[40:43]
	v_mfma_f32_16x16x32_bf16 v[28:31], v[128:131], v[204:207], v[28:31]
	v_mfma_f32_16x16x32_bf16 v[24:27], v[136:139], v[204:207], v[24:27]
	v_mfma_f32_16x16x32_bf16 v[12:15], v[128:131], v[212:215], v[12:15]
	v_mfma_f32_16x16x32_bf16 v[8:11], v[136:139], v[212:215], v[8:11]
	v_mfma_f32_16x16x32_bf16 v[60:63], v[132:135], v[192:195], v[60:63]
	v_mfma_f32_16x16x32_bf16 v[56:59], v[140:143], v[192:195], v[56:59]
	v_mfma_f32_16x16x32_bf16 v[44:47], v[132:135], v[200:203], v[44:47]
	v_mfma_f32_16x16x32_bf16 v[40:43], v[140:143], v[200:203], v[40:43]
	v_mfma_f32_16x16x32_bf16 v[28:31], v[132:135], v[208:211], v[28:31]
	v_mfma_f32_16x16x32_bf16 v[24:27], v[140:143], v[208:211], v[24:27]
	v_mfma_f32_16x16x32_bf16 v[12:15], v[132:135], v[216:219], v[12:15]
	v_mfma_f32_16x16x32_bf16 v[8:11], v[140:143], v[216:219], v[8:11]
	s_setprio 0
	s_setprio 1
	v_mfma_f32_16x16x32_bf16 v[52:55], v[144:147], v[188:191], v[52:55]
	v_mfma_f32_16x16x32_bf16 v[48:51], v[180:183], v[188:191], v[48:51]
	v_mfma_f32_16x16x32_bf16 v[36:39], v[144:147], v[196:199], v[36:39]
	v_mfma_f32_16x16x32_bf16 v[32:35], v[180:183], v[196:199], v[32:35]
	v_mfma_f32_16x16x32_bf16 v[20:23], v[144:147], v[204:207], v[20:23]
	v_mfma_f32_16x16x32_bf16 v[16:19], v[180:183], v[204:207], v[16:19]
	v_mfma_f32_16x16x32_bf16 v[4:7], v[144:147], v[212:215], v[4:7]
	v_mfma_f32_16x16x32_bf16 v[0:3], v[180:183], v[212:215], v[0:3]
	v_mfma_f32_16x16x32_bf16 v[52:55], v[148:151], v[192:195], v[52:55]
	v_mfma_f32_16x16x32_bf16 v[48:51], v[184:187], v[192:195], v[48:51]
	v_mfma_f32_16x16x32_bf16 v[36:39], v[148:151], v[200:203], v[36:39]
	v_mfma_f32_16x16x32_bf16 v[32:35], v[184:187], v[200:203], v[32:35]
	v_mfma_f32_16x16x32_bf16 v[20:23], v[148:151], v[208:211], v[20:23]
	v_mfma_f32_16x16x32_bf16 v[16:19], v[184:187], v[208:211], v[16:19]
	v_mfma_f32_16x16x32_bf16 v[4:7], v[148:151], v[216:219], v[4:7]
	v_mfma_f32_16x16x32_bf16 v[0:3], v[184:187], v[216:219], v[0:3]
	s_setprio 0
	s_barrier
	s_add_i32 s41, 0, 0x18000
	s_add_i32 s42, 0, 0x1c000
	v_add_u32_e32 v140, s41, v174
	v_add_u32_e32 v184, s42, v174
	ds_read_b128 v[128:131], v140
	ds_read_b128 v[132:135], v140 offset:1024
	ds_read_b128 v[136:139], v140 offset:2048
	ds_read_b128 v[140:143], v140 offset:3072
	ds_read_b128 v[144:147], v184
	ds_read_b128 v[148:151], v184 offset:1024
	ds_read_b128 v[180:183], v184 offset:2048
	ds_read_b128 v[184:187], v184 offset:3072
	ds_read_b128 v[188:191], v178 offset:32768
	ds_read_b128 v[192:195], v178 offset:33792
	ds_read_b128 v[196:199], v178 offset:34816
	ds_read_b128 v[200:203], v178 offset:35840
	ds_read_b128 v[204:207], v178 offset:36864
	ds_read_b128 v[208:211], v178 offset:37888
	ds_read_b128 v[212:215], v178 offset:38912
	ds_read_b128 v[216:219], v178 offset:39936
	s_add_u32 s34, s34, 0x100000
	s_addc_u32 s35, s35, 0
	s_mov_b32 m0, s60
	s_nop 0
	global_load_lds_dwordx4 v152, s[34:35]
	s_mov_b32 m0, s61
	s_nop 0
	global_load_lds_dwordx4 v156, s[34:35]
	s_waitcnt vmcnt(8)
	s_waitcnt lgkmcnt(0)
	s_setprio 1
	s_waitcnt lgkmcnt(0)
	v_mfma_f32_16x16x32_bf16 v[124:127], v[128:131], v[188:191], v[124:127]
	v_mfma_f32_16x16x32_bf16 v[120:123], v[136:139], v[188:191], v[120:123]
	v_mfma_f32_16x16x32_bf16 v[108:111], v[128:131], v[196:199], v[108:111]
	s_barrier
	v_mfma_f32_16x16x32_bf16 v[104:107], v[136:139], v[196:199], v[104:107]
	v_mfma_f32_16x16x32_bf16 v[92:95], v[128:131], v[204:207], v[92:95]
	v_mfma_f32_16x16x32_bf16 v[88:91], v[136:139], v[204:207], v[88:91]
	v_mfma_f32_16x16x32_bf16 v[76:79], v[128:131], v[212:215], v[76:79]
	v_mfma_f32_16x16x32_bf16 v[72:75], v[136:139], v[212:215], v[72:75]
	v_mfma_f32_16x16x32_bf16 v[124:127], v[132:135], v[192:195], v[124:127]
	v_mfma_f32_16x16x32_bf16 v[120:123], v[140:143], v[192:195], v[120:123]
	v_mfma_f32_16x16x32_bf16 v[108:111], v[132:135], v[200:203], v[108:111]
	v_mfma_f32_16x16x32_bf16 v[104:107], v[140:143], v[200:203], v[104:107]
	v_mfma_f32_16x16x32_bf16 v[92:95], v[132:135], v[208:211], v[92:95]
	v_mfma_f32_16x16x32_bf16 v[88:91], v[140:143], v[208:211], v[88:91]
	v_mfma_f32_16x16x32_bf16 v[76:79], v[132:135], v[216:219], v[76:79]
	v_mfma_f32_16x16x32_bf16 v[72:75], v[140:143], v[216:219], v[72:75]
	s_setprio 0
	s_setprio 1
	v_mfma_f32_16x16x32_bf16 v[116:119], v[144:147], v[188:191], v[116:119]
	v_mfma_f32_16x16x32_bf16 v[112:115], v[180:183], v[188:191], v[112:115]
	v_mfma_f32_16x16x32_bf16 v[100:103], v[144:147], v[196:199], v[100:103]
	v_mfma_f32_16x16x32_bf16 v[96:99], v[180:183], v[196:199], v[96:99]
	v_mfma_f32_16x16x32_bf16 v[84:87], v[144:147], v[204:207], v[84:87]
	v_mfma_f32_16x16x32_bf16 v[80:83], v[180:183], v[204:207], v[80:83]
	v_mfma_f32_16x16x32_bf16 v[68:71], v[144:147], v[212:215], v[68:71]
	v_mfma_f32_16x16x32_bf16 v[64:67], v[180:183], v[212:215], v[64:67]
	v_mfma_f32_16x16x32_bf16 v[116:119], v[148:151], v[192:195], v[116:119]
	v_mfma_f32_16x16x32_bf16 v[112:115], v[184:187], v[192:195], v[112:115]
	v_mfma_f32_16x16x32_bf16 v[100:103], v[148:151], v[200:203], v[100:103]
	v_mfma_f32_16x16x32_bf16 v[96:99], v[184:187], v[200:203], v[96:99]
	v_mfma_f32_16x16x32_bf16 v[84:87], v[148:151], v[208:211], v[84:87]
	v_mfma_f32_16x16x32_bf16 v[80:83], v[184:187], v[208:211], v[80:83]
	v_mfma_f32_16x16x32_bf16 v[68:71], v[148:151], v[216:219], v[68:71]
	v_mfma_f32_16x16x32_bf16 v[64:67], v[184:187], v[216:219], v[64:67]
	s_setprio 0
	s_barrier
	ds_read_b128 v[188:191], v178 offset:49152
	ds_read_b128 v[192:195], v178 offset:50176
	ds_read_b128 v[196:199], v178 offset:51200
	ds_read_b128 v[200:203], v178 offset:52224
	ds_read_b128 v[204:207], v178 offset:53248
	ds_read_b128 v[208:211], v178 offset:54272
	ds_read_b128 v[212:215], v178 offset:55296
	ds_read_b128 v[216:219], v178 offset:56320
	s_add_i32 s34, s41, s33
	v_lshl_add_u64 v[172:173], v[172:173], 0, s[16:17]
	s_mov_b32 m0, s34
	s_nop 0
	global_load_lds_dwordx4 v[172:173], off
	s_add_i32 m0, s34, 0x2000
	s_add_u32 s30, s30, 0x100800
	v_lshl_add_u64 v[172:173], v[220:221], 0, s[16:17]
	s_addc_u32 s31, s31, 0
	s_add_i32 s34, s42, s33
	global_load_lds_dwordx4 v[172:173], off
	v_lshl_add_u64 v[172:173], s[30:31], 0, v[154:155]
	s_mov_b32 m0, s34
	s_nop 0
	global_load_lds_dwordx4 v[172:173], off
	v_lshl_add_u64 v[172:173], s[30:31], 0, v[158:159]
	s_add_i32 m0, s34, 0x2000
	s_nop 0
	global_load_lds_dwordx4 v[172:173], off
	v_lshl_add_u64 v[172:173], v[222:223], 0, s[18:19]
	s_mov_b32 m0, s63
	s_nop 0
	global_load_lds_dwordx4 v[172:173], off
	v_lshl_add_u64 v[172:173], v[224:225], 0, s[18:19]
	s_mov_b32 m0, s64
	s_nop 0
	global_load_lds_dwordx4 v[172:173], off
	s_waitcnt vmcnt(8)
	s_waitcnt lgkmcnt(0)
	s_setprio 1
	s_waitcnt lgkmcnt(0)
	v_mfma_f32_16x16x32_bf16 v[60:63], v[128:131], v[188:191], v[60:63]
	v_mfma_f32_16x16x32_bf16 v[56:59], v[136:139], v[188:191], v[56:59]
	v_mfma_f32_16x16x32_bf16 v[44:47], v[128:131], v[196:199], v[44:47]
	s_barrier
	v_mfma_f32_16x16x32_bf16 v[40:43], v[136:139], v[196:199], v[40:43]
	v_mfma_f32_16x16x32_bf16 v[28:31], v[128:131], v[204:207], v[28:31]
	v_mfma_f32_16x16x32_bf16 v[24:27], v[136:139], v[204:207], v[24:27]
	v_mfma_f32_16x16x32_bf16 v[12:15], v[128:131], v[212:215], v[12:15]
	v_mfma_f32_16x16x32_bf16 v[8:11], v[136:139], v[212:215], v[8:11]
	v_mfma_f32_16x16x32_bf16 v[60:63], v[132:135], v[192:195], v[60:63]
	v_mfma_f32_16x16x32_bf16 v[56:59], v[140:143], v[192:195], v[56:59]
	v_mfma_f32_16x16x32_bf16 v[44:47], v[132:135], v[200:203], v[44:47]
	v_mfma_f32_16x16x32_bf16 v[40:43], v[140:143], v[200:203], v[40:43]
	v_mfma_f32_16x16x32_bf16 v[28:31], v[132:135], v[208:211], v[28:31]
	v_mfma_f32_16x16x32_bf16 v[24:27], v[140:143], v[208:211], v[24:27]
	v_mfma_f32_16x16x32_bf16 v[12:15], v[132:135], v[216:219], v[12:15]
	v_mfma_f32_16x16x32_bf16 v[8:11], v[140:143], v[216:219], v[8:11]
	s_setprio 0
	s_setprio 1
	v_mfma_f32_16x16x32_bf16 v[52:55], v[144:147], v[188:191], v[52:55]
	v_mfma_f32_16x16x32_bf16 v[48:51], v[180:183], v[188:191], v[48:51]
	v_mfma_f32_16x16x32_bf16 v[36:39], v[144:147], v[196:199], v[36:39]
	v_mfma_f32_16x16x32_bf16 v[32:35], v[180:183], v[196:199], v[32:35]
	v_mfma_f32_16x16x32_bf16 v[20:23], v[144:147], v[204:207], v[20:23]
	v_mfma_f32_16x16x32_bf16 v[16:19], v[180:183], v[204:207], v[16:19]
	v_mfma_f32_16x16x32_bf16 v[4:7], v[144:147], v[212:215], v[4:7]
	v_mfma_f32_16x16x32_bf16 v[0:3], v[180:183], v[212:215], v[0:3]
	v_mfma_f32_16x16x32_bf16 v[52:55], v[148:151], v[192:195], v[52:55]
	v_mfma_f32_16x16x32_bf16 v[48:51], v[184:187], v[192:195], v[48:51]
	v_mfma_f32_16x16x32_bf16 v[36:39], v[148:151], v[200:203], v[36:39]
	v_mfma_f32_16x16x32_bf16 v[32:35], v[184:187], v[200:203], v[32:35]
	v_mfma_f32_16x16x32_bf16 v[20:23], v[148:151], v[208:211], v[20:23]
	v_mfma_f32_16x16x32_bf16 v[16:19], v[184:187], v[208:211], v[16:19]
	v_mfma_f32_16x16x32_bf16 v[4:7], v[148:151], v[216:219], v[4:7]
	v_mfma_f32_16x16x32_bf16 v[0:3], v[184:187], v[216:219], v[0:3]
	s_setprio 0
	s_barrier
	s_add_i32 s40, s40, 2
	s_add_u32 s38, s38, 0x1000
	s_addc_u32 s39, s39, 0
	s_add_u32 s28, s28, 0x100
	s_addc_u32 s29, s29, 0
	s_cmp_gt_u32 s40, 61
	s_cbranch_scc0 .LBB0_1202
	s_and_b64 vcc, exec, s[10:11]
	s_cbranch_vccz .LBB0_1205
	s_barrier

.LBB0_1263:
	ds_read_b128 v[146:149], v152
	ds_read_b128 v[156:159], v152 offset:1024
	ds_read_b128 v[160:163], v152 offset:2048
	ds_read_b128 v[164:167], v152 offset:3072
	ds_read_b128 v[168:171], v153
	ds_read_b128 v[172:175], v153 offset:1024
	ds_read_b128 v[176:179], v153 offset:2048
	ds_read_b128 v[180:183], v153 offset:3072
	ds_read_b128 v[184:187], v154
	ds_read_b128 v[188:191], v154 offset:1024
	ds_read_b128 v[192:195], v154 offset:2048
	ds_read_b128 v[196:199], v154 offset:3072
	ds_read_b128 v[200:203], v154 offset:4096
	ds_read_b128 v[204:207], v154 offset:5120
	ds_read_b128 v[208:211], v154 offset:6144
	ds_read_b128 v[212:215], v154 offset:7168
	s_add_u32 s22, s20, 0x100
	s_addc_u32 s23, s21, 0
	s_cmp_eq_u32 s46, 12
	s_cselect_b32 s27, s5, s23
	s_cselect_b32 s26, s4, s22
	s_cselect_b32 s25, s19, s15
	s_cselect_b32 s24, s18, s6
	v_lshl_add_u64 v[216:217], s[20:21], 0, v[136:137]
	s_add_i32 m0, s17, 0xc000
	s_nop 0
	global_load_lds_dwordx4 v[216:217], off
	v_lshl_add_u64 v[216:217], s[20:21], 0, v[138:139]
	s_add_i32 m0, s17, 0xe000
	s_nop 0
	global_load_lds_dwordx4 v[216:217], off
	s_waitcnt vmcnt(8)
	s_waitcnt lgkmcnt(0)
	s_setprio 1
	s_waitcnt lgkmcnt(0)
	v_mfma_f32_16x16x32_bf16 v[124:127], v[146:149], v[184:187], v[124:127]
	v_mfma_f32_16x16x32_bf16 v[120:123], v[160:163], v[184:187], v[120:123]
	v_mfma_f32_16x16x32_bf16 v[112:115], v[146:149], v[192:195], v[112:115]
	s_barrier
	v_mfma_f32_16x16x32_bf16 v[104:107], v[160:163], v[192:195], v[104:107]
	v_mfma_f32_16x16x32_bf16 v[96:99], v[146:149], v[200:203], v[96:99]
	v_mfma_f32_16x16x32_bf16 v[88:91], v[160:163], v[200:203], v[88:91]
	v_mfma_f32_16x16x32_bf16 v[80:83], v[146:149], v[208:211], v[80:83]
	v_mfma_f32_16x16x32_bf16 v[72:75], v[160:163], v[208:211], v[72:75]
	v_mfma_f32_16x16x32_bf16 v[124:127], v[156:159], v[188:191], v[124:127]
	v_mfma_f32_16x16x32_bf16 v[120:123], v[164:167], v[188:191], v[120:123]
	v_mfma_f32_16x16x32_bf16 v[112:115], v[156:159], v[196:199], v[112:115]
	v_mfma_f32_16x16x32_bf16 v[104:107], v[164:167], v[196:199], v[104:107]
	v_mfma_f32_16x16x32_bf16 v[96:99], v[156:159], v[204:207], v[96:99]
	v_mfma_f32_16x16x32_bf16 v[88:91], v[164:167], v[204:207], v[88:91]
	v_mfma_f32_16x16x32_bf16 v[80:83], v[156:159], v[212:215], v[80:83]
	v_mfma_f32_16x16x32_bf16 v[72:75], v[164:167], v[212:215], v[72:75]
	s_setprio 0
	s_setprio 1
	v_mfma_f32_16x16x32_bf16 v[116:119], v[168:171], v[184:187], v[116:119]
	v_mfma_f32_16x16x32_bf16 v[108:111], v[176:179], v[184:187], v[108:111]
	v_mfma_f32_16x16x32_bf16 v[100:103], v[168:171], v[192:195], v[100:103]
	v_mfma_f32_16x16x32_bf16 v[92:95], v[176:179], v[192:195], v[92:95]
	v_mfma_f32_16x16x32_bf16 v[84:87], v[168:171], v[200:203], v[84:87]
	v_mfma_f32_16x16x32_bf16 v[76:79], v[176:179], v[200:203], v[76:79]
	v_mfma_f32_16x16x32_bf16 v[68:71], v[168:171], v[208:211], v[68:71]
	v_mfma_f32_16x16x32_bf16 v[64:67], v[176:179], v[208:211], v[64:67]
	v_mfma_f32_16x16x32_bf16 v[116:119], v[172:175], v[188:191], v[116:119]
	v_mfma_f32_16x16x32_bf16 v[108:111], v[180:183], v[188:191], v[108:111]
	v_mfma_f32_16x16x32_bf16 v[100:103], v[172:175], v[196:199], v[100:103]
	v_mfma_f32_16x16x32_bf16 v[92:95], v[180:183], v[196:199], v[92:95]
	v_mfma_f32_16x16x32_bf16 v[84:87], v[172:175], v[204:207], v[84:87]
	v_mfma_f32_16x16x32_bf16 v[76:79], v[180:183], v[204:207], v[76:79]
	v_mfma_f32_16x16x32_bf16 v[68:71], v[172:175], v[212:215], v[68:71]
	v_mfma_f32_16x16x32_bf16 v[64:67], v[180:183], v[212:215], v[64:67]
	s_setprio 0
	s_barrier
	ds_read_b128 v[184:187], v154 offset:16384
	ds_read_b128 v[188:191], v154 offset:17408
	ds_read_b128 v[192:195], v154 offset:18432
	ds_read_b128 v[196:199], v154 offset:19456
	ds_read_b128 v[200:203], v154 offset:20480
	ds_read_b128 v[204:207], v154 offset:21504
	ds_read_b128 v[208:211], v154 offset:22528
	ds_read_b128 v[212:215], v154 offset:23552
	s_add_i32 s20, s41, s33
	v_lshl_add_u64 v[216:217], s[24:25], 0, v[130:131]
	s_mov_b32 m0, s20
	v_lshl_add_u64 v[218:219], s[24:25], 0, v[134:135]
	global_load_lds_dwordx4 v[216:217], off
	s_add_i32 m0, s20, 0x2000
	s_add_u32 s20, s24, 0x200000
	s_addc_u32 s21, s25, 0
	s_add_i32 s47, s42, s33
	global_load_lds_dwordx4 v[218:219], off
	s_mov_b32 m0, s47
	v_lshl_add_u64 v[220:221], s[26:27], 0, v[128:129]
	global_load_lds_dwordx4 v130, s[20:21]
	s_add_i32 m0, s47, 0x2000
	v_lshl_add_u64 v[222:223], s[26:27], 0, v[132:133]
	global_load_lds_dwordx4 v134, s[20:21]
	s_mov_b32 m0, s17
	s_nop 0
	global_load_lds_dwordx4 v[220:221], off
	s_mov_b32 m0, s34
	s_nop 0
	global_load_lds_dwordx4 v[222:223], off
	s_waitcnt vmcnt(8)
	s_waitcnt lgkmcnt(0)
	s_setprio 1
	s_waitcnt lgkmcnt(0)
	v_mfma_f32_16x16x32_bf16 v[60:63], v[146:149], v[184:187], v[60:63]
	v_mfma_f32_16x16x32_bf16 v[56:59], v[160:163], v[184:187], v[56:59]
	v_mfma_f32_16x16x32_bf16 v[48:51], v[146:149], v[192:195], v[48:51]
	s_barrier
	v_mfma_f32_16x16x32_bf16 v[40:43], v[160:163], v[192:195], v[40:43]
	v_mfma_f32_16x16x32_bf16 v[32:35], v[146:149], v[200:203], v[32:35]
	v_mfma_f32_16x16x32_bf16 v[24:27], v[160:163], v[200:203], v[24:27]
	v_mfma_f32_16x16x32_bf16 v[16:19], v[146:149], v[208:211], v[16:19]
	v_mfma_f32_16x16x32_bf16 v[8:11], v[160:163], v[208:211], v[8:11]
	v_mfma_f32_16x16x32_bf16 v[60:63], v[156:159], v[188:191], v[60:63]
	v_mfma_f32_16x16x32_bf16 v[56:59], v[164:167], v[188:191], v[56:59]
	v_mfma_f32_16x16x32_bf16 v[48:51], v[156:159], v[196:199], v[48:51]
	v_mfma_f32_16x16x32_bf16 v[40:43], v[164:167], v[196:199], v[40:43]
	v_mfma_f32_16x16x32_bf16 v[32:35], v[156:159], v[204:207], v[32:35]
	v_mfma_f32_16x16x32_bf16 v[24:27], v[164:167], v[204:207], v[24:27]
	v_mfma_f32_16x16x32_bf16 v[16:19], v[156:159], v[212:215], v[16:19]
	v_mfma_f32_16x16x32_bf16 v[8:11], v[164:167], v[212:215], v[8:11]
	s_setprio 0
	s_setprio 1
	v_mfma_f32_16x16x32_bf16 v[52:55], v[168:171], v[184:187], v[52:55]
	v_mfma_f32_16x16x32_bf16 v[44:47], v[176:179], v[184:187], v[44:47]
	v_mfma_f32_16x16x32_bf16 v[36:39], v[168:171], v[192:195], v[36:39]
	v_mfma_f32_16x16x32_bf16 v[28:31], v[176:179], v[192:195], v[28:31]
	v_mfma_f32_16x16x32_bf16 v[20:23], v[168:171], v[200:203], v[20:23]
	v_mfma_f32_16x16x32_bf16 v[12:15], v[176:179], v[200:203], v[12:15]
	v_mfma_f32_16x16x32_bf16 v[4:7], v[168:171], v[208:211], v[4:7]
	v_mfma_f32_16x16x32_bf16 v[0:3], v[176:179], v[208:211], v[0:3]
	v_mfma_f32_16x16x32_bf16 v[52:55], v[172:175], v[188:191], v[52:55]
	v_mfma_f32_16x16x32_bf16 v[44:47], v[180:183], v[188:191], v[44:47]
	v_mfma_f32_16x16x32_bf16 v[36:39], v[172:175], v[196:199], v[36:39]
	v_mfma_f32_16x16x32_bf16 v[28:31], v[180:183], v[196:199], v[28:31]
	v_mfma_f32_16x16x32_bf16 v[20:23], v[172:175], v[204:207], v[20:23]
	v_mfma_f32_16x16x32_bf16 v[12:15], v[180:183], v[204:207], v[12:15]
	v_mfma_f32_16x16x32_bf16 v[4:7], v[172:175], v[212:215], v[4:7]
	v_mfma_f32_16x16x32_bf16 v[0:3], v[180:183], v[212:215], v[0:3]
	s_setprio 0
	s_barrier
	s_add_i32 s47, 0, 0x18000
	v_add_u32_e32 v144, s47, v145
	s_add_i32 s48, 0, 0x1c000
	ds_read_b128 v[146:149], v144
	ds_read_b128 v[156:159], v144 offset:1024
	ds_read_b128 v[160:163], v144 offset:2048
	ds_read_b128 v[164:167], v144 offset:3072
	v_add_u32_e32 v144, s48, v145
	ds_read_b128 v[168:171], v144
	ds_read_b128 v[172:175], v144 offset:1024
	ds_read_b128 v[176:179], v144 offset:2048
	ds_read_b128 v[180:183], v144 offset:3072
	ds_read_b128 v[184:187], v154 offset:32768
	ds_read_b128 v[188:191], v154 offset:33792
	ds_read_b128 v[192:195], v154 offset:34816
	ds_read_b128 v[196:199], v154 offset:35840
	ds_read_b128 v[200:203], v154 offset:36864
	ds_read_b128 v[204:207], v154 offset:37888
	ds_read_b128 v[208:211], v154 offset:38912
	ds_read_b128 v[212:215], v154 offset:39936
	s_add_u32 s20, s26, 0x200000
	s_addc_u32 s21, s27, 0
	s_mov_b32 m0, s35
	s_nop 0
	global_load_lds_dwordx4 v128, s[20:21]
	s_mov_b32 m0, s36
	s_nop 0
	global_load_lds_dwordx4 v132, s[20:21]
	s_waitcnt vmcnt(8)
	s_waitcnt lgkmcnt(0)
	s_setprio 1
	s_waitcnt lgkmcnt(0)
	v_mfma_f32_16x16x32_bf16 v[124:127], v[146:149], v[184:187], v[124:127]
	v_mfma_f32_16x16x32_bf16 v[120:123], v[160:163], v[184:187], v[120:123]
	v_mfma_f32_16x16x32_bf16 v[112:115], v[146:149], v[192:195], v[112:115]
	s_barrier
	v_mfma_f32_16x16x32_bf16 v[104:107], v[160:163], v[192:195], v[104:107]
	v_mfma_f32_16x16x32_bf16 v[96:99], v[146:149], v[200:203], v[96:99]
	v_mfma_f32_16x16x32_bf16 v[88:91], v[160:163], v[200:203], v[88:91]
	v_mfma_f32_16x16x32_bf16 v[80:83], v[146:149], v[208:211], v[80:83]
	v_mfma_f32_16x16x32_bf16 v[72:75], v[160:163], v[208:211], v[72:75]
	v_mfma_f32_16x16x32_bf16 v[124:127], v[156:159], v[188:191], v[124:127]
	v_mfma_f32_16x16x32_bf16 v[120:123], v[164:167], v[188:191], v[120:123]
	v_mfma_f32_16x16x32_bf16 v[112:115], v[156:159], v[196:199], v[112:115]
	v_mfma_f32_16x16x32_bf16 v[104:107], v[164:167], v[196:199], v[104:107]
	v_mfma_f32_16x16x32_bf16 v[96:99], v[156:159], v[204:207], v[96:99]
	v_mfma_f32_16x16x32_bf16 v[88:91], v[164:167], v[204:207], v[88:91]
	v_mfma_f32_16x16x32_bf16 v[80:83], v[156:159], v[212:215], v[80:83]
	v_mfma_f32_16x16x32_bf16 v[72:75], v[164:167], v[212:215], v[72:75]
	s_setprio 0
	s_setprio 1
	v_mfma_f32_16x16x32_bf16 v[116:119], v[168:171], v[184:187], v[116:119]
	v_mfma_f32_16x16x32_bf16 v[108:111], v[176:179], v[184:187], v[108:111]
	v_mfma_f32_16x16x32_bf16 v[100:103], v[168:171], v[192:195], v[100:103]
	v_mfma_f32_16x16x32_bf16 v[92:95], v[176:179], v[192:195], v[92:95]
	v_mfma_f32_16x16x32_bf16 v[84:87], v[168:171], v[200:203], v[84:87]
	v_mfma_f32_16x16x32_bf16 v[76:79], v[176:179], v[200:203], v[76:79]
	v_mfma_f32_16x16x32_bf16 v[68:71], v[168:171], v[208:211], v[68:71]
	v_mfma_f32_16x16x32_bf16 v[64:67], v[176:179], v[208:211], v[64:67]
	v_mfma_f32_16x16x32_bf16 v[116:119], v[172:175], v[188:191], v[116:119]
	v_mfma_f32_16x16x32_bf16 v[108:111], v[180:183], v[188:191], v[108:111]
	v_mfma_f32_16x16x32_bf16 v[100:103], v[172:175], v[196:199], v[100:103]
	v_mfma_f32_16x16x32_bf16 v[92:95], v[180:183], v[196:199], v[92:95]
	v_mfma_f32_16x16x32_bf16 v[84:87], v[172:175], v[204:207], v[84:87]
	v_mfma_f32_16x16x32_bf16 v[76:79], v[180:183], v[204:207], v[76:79]
	v_mfma_f32_16x16x32_bf16 v[68:71], v[172:175], v[212:215], v[68:71]
	v_mfma_f32_16x16x32_bf16 v[64:67], v[180:183], v[212:215], v[64:67]
	s_setprio 0
	s_barrier
	ds_read_b128 v[184:187], v154 offset:49152
	ds_read_b128 v[188:191], v154 offset:50176
	ds_read_b128 v[192:195], v154 offset:51200
	ds_read_b128 v[196:199], v154 offset:52224
	ds_read_b128 v[200:203], v154 offset:53248
	ds_read_b128 v[204:207], v154 offset:54272
	ds_read_b128 v[208:211], v154 offset:55296
	ds_read_b128 v[212:215], v154 offset:56320
	s_add_i32 s20, s47, s33
	v_lshl_add_u64 v[216:217], v[216:217], 0, s[12:13]
	s_mov_b32 m0, s20
	s_nop 0
	global_load_lds_dwordx4 v[216:217], off
	s_add_i32 m0, s20, 0x2000
	s_add_u32 s20, s24, 0x200080
	v_lshl_add_u64 v[218:219], v[218:219], 0, s[12:13]
	s_addc_u32 s21, s25, 0
	s_add_i32 s24, s48, s33
	global_load_lds_dwordx4 v[218:219], off
	s_mov_b32 m0, s24
	s_nop 0
	global_load_lds_dwordx4 v130, s[20:21]
	s_add_i32 m0, s24, 0x2000
	s_nop 0
	global_load_lds_dwordx4 v134, s[20:21]
	v_lshl_add_u64 v[220:221], v[220:221], 0, s[12:13]
	s_mov_b32 m0, s37
	s_nop 0
	global_load_lds_dwordx4 v[220:221], off
	v_lshl_add_u64 v[222:223], v[222:223], 0, s[12:13]
	s_mov_b32 m0, s38
	s_nop 0
	global_load_lds_dwordx4 v[222:223], off
	s_waitcnt vmcnt(8)
	s_waitcnt lgkmcnt(0)
	s_setprio 1
	s_waitcnt lgkmcnt(0)
	v_mfma_f32_16x16x32_bf16 v[60:63], v[146:149], v[184:187], v[60:63]
	v_mfma_f32_16x16x32_bf16 v[56:59], v[160:163], v[184:187], v[56:59]
	v_mfma_f32_16x16x32_bf16 v[48:51], v[146:149], v[192:195], v[48:51]
	s_barrier
	v_mfma_f32_16x16x32_bf16 v[40:43], v[160:163], v[192:195], v[40:43]
	v_mfma_f32_16x16x32_bf16 v[32:35], v[146:149], v[200:203], v[32:35]
	v_mfma_f32_16x16x32_bf16 v[24:27], v[160:163], v[200:203], v[24:27]
	v_mfma_f32_16x16x32_bf16 v[16:19], v[146:149], v[208:211], v[16:19]
	v_mfma_f32_16x16x32_bf16 v[8:11], v[160:163], v[208:211], v[8:11]
	v_mfma_f32_16x16x32_bf16 v[60:63], v[156:159], v[188:191], v[60:63]
	v_mfma_f32_16x16x32_bf16 v[56:59], v[164:167], v[188:191], v[56:59]
	v_mfma_f32_16x16x32_bf16 v[48:51], v[156:159], v[196:199], v[48:51]
	v_mfma_f32_16x16x32_bf16 v[40:43], v[164:167], v[196:199], v[40:43]
	v_mfma_f32_16x16x32_bf16 v[32:35], v[156:159], v[204:207], v[32:35]
	v_mfma_f32_16x16x32_bf16 v[24:27], v[164:167], v[204:207], v[24:27]
	v_mfma_f32_16x16x32_bf16 v[16:19], v[156:159], v[212:215], v[16:19]
	v_mfma_f32_16x16x32_bf16 v[8:11], v[164:167], v[212:215], v[8:11]
	s_setprio 0
	s_setprio 1
	v_mfma_f32_16x16x32_bf16 v[52:55], v[168:171], v[184:187], v[52:55]
	v_mfma_f32_16x16x32_bf16 v[44:47], v[176:179], v[184:187], v[44:47]
	v_mfma_f32_16x16x32_bf16 v[36:39], v[168:171], v[192:195], v[36:39]
	v_mfma_f32_16x16x32_bf16 v[28:31], v[176:179], v[192:195], v[28:31]
	v_mfma_f32_16x16x32_bf16 v[20:23], v[168:171], v[200:203], v[20:23]
	v_mfma_f32_16x16x32_bf16 v[12:15], v[176:179], v[200:203], v[12:15]
	v_mfma_f32_16x16x32_bf16 v[4:7], v[168:171], v[208:211], v[4:7]
	v_mfma_f32_16x16x32_bf16 v[0:3], v[176:179], v[208:211], v[0:3]
	v_mfma_f32_16x16x32_bf16 v[52:55], v[172:175], v[188:191], v[52:55]
	v_mfma_f32_16x16x32_bf16 v[44:47], v[180:183], v[188:191], v[44:47]
	v_mfma_f32_16x16x32_bf16 v[36:39], v[172:175], v[196:199], v[36:39]
	v_mfma_f32_16x16x32_bf16 v[28:31], v[180:183], v[196:199], v[28:31]
	v_mfma_f32_16x16x32_bf16 v[20:23], v[172:175], v[204:207], v[20:23]
	v_mfma_f32_16x16x32_bf16 v[12:15], v[180:183], v[204:207], v[12:15]
	v_mfma_f32_16x16x32_bf16 v[4:7], v[172:175], v[212:215], v[4:7]
	v_mfma_f32_16x16x32_bf16 v[0:3], v[180:183], v[212:215], v[0:3]
	s_setprio 0
	s_barrier
	s_add_i32 s46, s46, 2
	s_add_u32 s6, s6, 0x100
	s_addc_u32 s15, s15, 0
	s_cmp_gt_u32 s46, 13
	s_mov_b64 s[20:21], s[22:23]
	s_cbranch_scc0 .LBB0_1263
	s_and_b64 vcc, exec, s[8:9]
	s_cbranch_vccz .LBB0_1266
	s_barrier

.LBB0_1340:
	v_add_u32_e32 v166, s51, v152
	v_add_u32_e32 v182, s52, v152
	ds_read_b128 v[154:157], v166
	ds_read_b128 v[158:161], v166 offset:1024
	ds_read_b128 v[162:165], v166 offset:2048
	ds_read_b128 v[166:169], v166 offset:3072
	ds_read_b128 v[170:173], v182
	ds_read_b128 v[174:177], v182 offset:1024
	ds_read_b128 v[178:181], v182 offset:2048
	ds_read_b128 v[182:185], v182 offset:3072
	ds_read_b128 v[186:189], v153
	ds_read_b128 v[190:193], v153 offset:1024
	ds_read_b128 v[194:197], v153 offset:2048
	ds_read_b128 v[198:201], v153 offset:3072
	ds_read_b128 v[202:205], v153 offset:4096
	ds_read_b128 v[206:209], v153 offset:5120
	ds_read_b128 v[210:213], v153 offset:6144
	ds_read_b128 v[214:217], v153 offset:7168
	s_add_u32 s30, s10, s28
	s_addc_u32 s31, s11, s29
	s_cmp_eq_u32 s58, 60
	s_cselect_b32 s35, s23, s31
	s_cselect_b32 s34, s54, s30
	s_cselect_b32 s31, s21, s57
	s_cselect_b32 s30, s55, s56
	v_lshl_add_u64 v[218:219], s[10:11], 0, v[146:147]
	s_add_i32 m0, s44, 0xc000
	s_nop 0
	global_load_lds_dwordx4 v[218:219], off
	v_lshl_add_u64 v[218:219], s[10:11], 0, v[144:145]
	s_add_i32 m0, s44, 0xe000
	s_nop 0
	global_load_lds_dwordx4 v[218:219], off
	s_waitcnt vmcnt(8)
	s_waitcnt lgkmcnt(0)
	s_setprio 1
	s_waitcnt lgkmcnt(0)
	v_mfma_f32_16x16x32_bf16 v[124:127], v[154:157], v[186:189], v[124:127]
	v_mfma_f32_16x16x32_bf16 v[120:123], v[162:165], v[186:189], v[120:123]
	v_mfma_f32_16x16x32_bf16 v[108:111], v[154:157], v[194:197], v[108:111]
	s_barrier
	v_mfma_f32_16x16x32_bf16 v[104:107], v[162:165], v[194:197], v[104:107]
	v_mfma_f32_16x16x32_bf16 v[92:95], v[154:157], v[202:205], v[92:95]
	v_mfma_f32_16x16x32_bf16 v[88:91], v[162:165], v[202:205], v[88:91]
	v_mfma_f32_16x16x32_bf16 v[76:79], v[154:157], v[210:213], v[76:79]
	v_mfma_f32_16x16x32_bf16 v[72:75], v[162:165], v[210:213], v[72:75]
	v_mfma_f32_16x16x32_bf16 v[124:127], v[158:161], v[190:193], v[124:127]
	v_mfma_f32_16x16x32_bf16 v[120:123], v[166:169], v[190:193], v[120:123]
	v_mfma_f32_16x16x32_bf16 v[108:111], v[158:161], v[198:201], v[108:111]
	v_mfma_f32_16x16x32_bf16 v[104:107], v[166:169], v[198:201], v[104:107]
	v_mfma_f32_16x16x32_bf16 v[92:95], v[158:161], v[206:209], v[92:95]
	v_mfma_f32_16x16x32_bf16 v[88:91], v[166:169], v[206:209], v[88:91]
	v_mfma_f32_16x16x32_bf16 v[76:79], v[158:161], v[214:217], v[76:79]
	v_mfma_f32_16x16x32_bf16 v[72:75], v[166:169], v[214:217], v[72:75]
	s_setprio 0
	s_setprio 1
	v_mfma_f32_16x16x32_bf16 v[116:119], v[170:173], v[186:189], v[116:119]
	v_mfma_f32_16x16x32_bf16 v[112:115], v[178:181], v[186:189], v[112:115]
	v_mfma_f32_16x16x32_bf16 v[100:103], v[170:173], v[194:197], v[100:103]
	v_mfma_f32_16x16x32_bf16 v[96:99], v[178:181], v[194:197], v[96:99]
	v_mfma_f32_16x16x32_bf16 v[84:87], v[170:173], v[202:205], v[84:87]
	v_mfma_f32_16x16x32_bf16 v[80:83], v[178:181], v[202:205], v[80:83]
	v_mfma_f32_16x16x32_bf16 v[68:71], v[170:173], v[210:213], v[68:71]
	v_mfma_f32_16x16x32_bf16 v[64:67], v[178:181], v[210:213], v[64:67]
	v_mfma_f32_16x16x32_bf16 v[116:119], v[174:177], v[190:193], v[116:119]
	v_mfma_f32_16x16x32_bf16 v[112:115], v[182:185], v[190:193], v[112:115]
	v_mfma_f32_16x16x32_bf16 v[100:103], v[174:177], v[198:201], v[100:103]
	v_mfma_f32_16x16x32_bf16 v[96:99], v[182:185], v[198:201], v[96:99]
	v_mfma_f32_16x16x32_bf16 v[84:87], v[174:177], v[206:209], v[84:87]
	v_mfma_f32_16x16x32_bf16 v[80:83], v[182:185], v[206:209], v[80:83]
	v_mfma_f32_16x16x32_bf16 v[68:71], v[174:177], v[214:217], v[68:71]
	v_mfma_f32_16x16x32_bf16 v[64:67], v[182:185], v[214:217], v[64:67]
	s_setprio 0
	s_barrier
	ds_read_b128 v[186:189], v153 offset:16384
	ds_read_b128 v[190:193], v153 offset:17408
	ds_read_b128 v[194:197], v153 offset:18432
	ds_read_b128 v[198:201], v153 offset:19456
	ds_read_b128 v[202:205], v153 offset:20480
	ds_read_b128 v[206:209], v153 offset:21504
	ds_read_b128 v[210:213], v153 offset:22528
	ds_read_b128 v[214:217], v153 offset:23552
	s_add_i32 s59, s51, s43
	v_lshl_add_u64 v[218:219], s[30:31], 0, v[130:131]
	s_mov_b32 m0, s59
	v_lshl_add_u64 v[220:221], s[30:31], 0, v[134:135]
	global_load_lds_dwordx4 v[218:219], off
	s_add_i32 m0, s59, 0x2000
	s_add_u32 s60, s30, 0x100000
	s_addc_u32 s61, s31, 0
	s_add_i32 s59, s52, s43
	global_load_lds_dwordx4 v[220:221], off
	s_mov_b32 m0, s59
	v_lshl_add_u64 v[222:223], s[34:35], 0, v[128:129]
	global_load_lds_dwordx4 v130, s[60:61]
	s_add_i32 m0, s59, 0x2000
	v_lshl_add_u64 v[224:225], s[34:35], 0, v[132:133]
	global_load_lds_dwordx4 v134, s[60:61]
	s_mov_b32 m0, s44
	s_nop 0
	global_load_lds_dwordx4 v[222:223], off
	s_mov_b32 m0, s45
	s_nop 0
	global_load_lds_dwordx4 v[224:225], off
	s_waitcnt vmcnt(8)
	s_waitcnt lgkmcnt(0)
	s_setprio 1
	s_waitcnt lgkmcnt(0)
	v_mfma_f32_16x16x32_bf16 v[60:63], v[154:157], v[186:189], v[60:63]
	v_mfma_f32_16x16x32_bf16 v[56:59], v[162:165], v[186:189], v[56:59]
	v_mfma_f32_16x16x32_bf16 v[44:47], v[154:157], v[194:197], v[44:47]
	s_barrier
	v_mfma_f32_16x16x32_bf16 v[40:43], v[162:165], v[194:197], v[40:43]
	v_mfma_f32_16x16x32_bf16 v[28:31], v[154:157], v[202:205], v[28:31]
	v_mfma_f32_16x16x32_bf16 v[24:27], v[162:165], v[202:205], v[24:27]
	v_mfma_f32_16x16x32_bf16 v[12:15], v[154:157], v[210:213], v[12:15]
	v_mfma_f32_16x16x32_bf16 v[8:11], v[162:165], v[210:213], v[8:11]
	v_mfma_f32_16x16x32_bf16 v[60:63], v[158:161], v[190:193], v[60:63]
	v_mfma_f32_16x16x32_bf16 v[56:59], v[166:169], v[190:193], v[56:59]
	v_mfma_f32_16x16x32_bf16 v[44:47], v[158:161], v[198:201], v[44:47]
	v_mfma_f32_16x16x32_bf16 v[40:43], v[166:169], v[198:201], v[40:43]
	v_mfma_f32_16x16x32_bf16 v[28:31], v[158:161], v[206:209], v[28:31]
	v_mfma_f32_16x16x32_bf16 v[24:27], v[166:169], v[206:209], v[24:27]
	v_mfma_f32_16x16x32_bf16 v[12:15], v[158:161], v[214:217], v[12:15]
	v_mfma_f32_16x16x32_bf16 v[8:11], v[166:169], v[214:217], v[8:11]
	s_setprio 0
	s_setprio 1
	v_mfma_f32_16x16x32_bf16 v[52:55], v[170:173], v[186:189], v[52:55]
	v_mfma_f32_16x16x32_bf16 v[48:51], v[178:181], v[186:189], v[48:51]
	v_mfma_f32_16x16x32_bf16 v[36:39], v[170:173], v[194:197], v[36:39]
	v_mfma_f32_16x16x32_bf16 v[32:35], v[178:181], v[194:197], v[32:35]
	v_mfma_f32_16x16x32_bf16 v[20:23], v[170:173], v[202:205], v[20:23]
	v_mfma_f32_16x16x32_bf16 v[16:19], v[178:181], v[202:205], v[16:19]
	v_mfma_f32_16x16x32_bf16 v[4:7], v[170:173], v[210:213], v[4:7]
	v_mfma_f32_16x16x32_bf16 v[0:3], v[178:181], v[210:213], v[0:3]
	v_mfma_f32_16x16x32_bf16 v[52:55], v[174:177], v[190:193], v[52:55]
	v_mfma_f32_16x16x32_bf16 v[48:51], v[182:185], v[190:193], v[48:51]
	v_mfma_f32_16x16x32_bf16 v[36:39], v[174:177], v[198:201], v[36:39]
	v_mfma_f32_16x16x32_bf16 v[32:35], v[182:185], v[198:201], v[32:35]
	v_mfma_f32_16x16x32_bf16 v[20:23], v[174:177], v[206:209], v[20:23]
	v_mfma_f32_16x16x32_bf16 v[16:19], v[182:185], v[206:209], v[16:19]
	v_mfma_f32_16x16x32_bf16 v[4:7], v[174:177], v[214:217], v[4:7]
	v_mfma_f32_16x16x32_bf16 v[0:3], v[182:185], v[214:217], v[0:3]
	s_setprio 0
	s_barrier
	s_add_i32 s59, 0, 0x18000
	s_add_i32 s60, 0, 0x1c000
	v_add_u32_e32 v166, s59, v152
	v_add_u32_e32 v182, s60, v152
	ds_read_b128 v[154:157], v166
	ds_read_b128 v[158:161], v166 offset:1024
	ds_read_b128 v[162:165], v166 offset:2048
	ds_read_b128 v[166:169], v166 offset:3072
	ds_read_b128 v[170:173], v182
	ds_read_b128 v[174:177], v182 offset:1024
	ds_read_b128 v[178:181], v182 offset:2048
	ds_read_b128 v[182:185], v182 offset:3072
	ds_read_b128 v[186:189], v153 offset:32768
	ds_read_b128 v[190:193], v153 offset:33792
	ds_read_b128 v[194:197], v153 offset:34816
	ds_read_b128 v[198:201], v153 offset:35840
	ds_read_b128 v[202:205], v153 offset:36864
	ds_read_b128 v[206:209], v153 offset:37888
	ds_read_b128 v[210:213], v153 offset:38912
	ds_read_b128 v[214:217], v153 offset:39936
	s_add_u32 s34, s34, 0x100000
	s_addc_u32 s35, s35, 0
	s_mov_b32 m0, s46
	s_nop 0
	global_load_lds_dwordx4 v128, s[34:35]
	s_mov_b32 m0, s47
	s_nop 0
	global_load_lds_dwordx4 v132, s[34:35]
	s_waitcnt vmcnt(8)
	s_waitcnt lgkmcnt(0)
	s_setprio 1
	s_waitcnt lgkmcnt(0)
	v_mfma_f32_16x16x32_bf16 v[124:127], v[154:157], v[186:189], v[124:127]
	v_mfma_f32_16x16x32_bf16 v[120:123], v[162:165], v[186:189], v[120:123]
	v_mfma_f32_16x16x32_bf16 v[108:111], v[154:157], v[194:197], v[108:111]
	s_barrier
	v_mfma_f32_16x16x32_bf16 v[104:107], v[162:165], v[194:197], v[104:107]
	v_mfma_f32_16x16x32_bf16 v[92:95], v[154:157], v[202:205], v[92:95]
	v_mfma_f32_16x16x32_bf16 v[88:91], v[162:165], v[202:205], v[88:91]
	v_mfma_f32_16x16x32_bf16 v[76:79], v[154:157], v[210:213], v[76:79]
	v_mfma_f32_16x16x32_bf16 v[72:75], v[162:165], v[210:213], v[72:75]
	v_mfma_f32_16x16x32_bf16 v[124:127], v[158:161], v[190:193], v[124:127]
	v_mfma_f32_16x16x32_bf16 v[120:123], v[166:169], v[190:193], v[120:123]
	v_mfma_f32_16x16x32_bf16 v[108:111], v[158:161], v[198:201], v[108:111]
	v_mfma_f32_16x16x32_bf16 v[104:107], v[166:169], v[198:201], v[104:107]
	v_mfma_f32_16x16x32_bf16 v[92:95], v[158:161], v[206:209], v[92:95]
	v_mfma_f32_16x16x32_bf16 v[88:91], v[166:169], v[206:209], v[88:91]
	v_mfma_f32_16x16x32_bf16 v[76:79], v[158:161], v[214:217], v[76:79]
	v_mfma_f32_16x16x32_bf16 v[72:75], v[166:169], v[214:217], v[72:75]
	s_setprio 0
	s_setprio 1
	v_mfma_f32_16x16x32_bf16 v[116:119], v[170:173], v[186:189], v[116:119]
	v_mfma_f32_16x16x32_bf16 v[112:115], v[178:181], v[186:189], v[112:115]
	v_mfma_f32_16x16x32_bf16 v[100:103], v[170:173], v[194:197], v[100:103]
	v_mfma_f32_16x16x32_bf16 v[96:99], v[178:181], v[194:197], v[96:99]
	v_mfma_f32_16x16x32_bf16 v[84:87], v[170:173], v[202:205], v[84:87]
	v_mfma_f32_16x16x32_bf16 v[80:83], v[178:181], v[202:205], v[80:83]
	v_mfma_f32_16x16x32_bf16 v[68:71], v[170:173], v[210:213], v[68:71]
	v_mfma_f32_16x16x32_bf16 v[64:67], v[178:181], v[210:213], v[64:67]
	v_mfma_f32_16x16x32_bf16 v[116:119], v[174:177], v[190:193], v[116:119]
	v_mfma_f32_16x16x32_bf16 v[112:115], v[182:185], v[190:193], v[112:115]
	v_mfma_f32_16x16x32_bf16 v[100:103], v[174:177], v[198:201], v[100:103]
	v_mfma_f32_16x16x32_bf16 v[96:99], v[182:185], v[198:201], v[96:99]
	v_mfma_f32_16x16x32_bf16 v[84:87], v[174:177], v[206:209], v[84:87]
	v_mfma_f32_16x16x32_bf16 v[80:83], v[182:185], v[206:209], v[80:83]
	v_mfma_f32_16x16x32_bf16 v[68:71], v[174:177], v[214:217], v[68:71]
	v_mfma_f32_16x16x32_bf16 v[64:67], v[182:185], v[214:217], v[64:67]
	s_setprio 0
	s_barrier
	ds_read_b128 v[186:189], v153 offset:49152
	ds_read_b128 v[190:193], v153 offset:50176
	ds_read_b128 v[194:197], v153 offset:51200
	ds_read_b128 v[198:201], v153 offset:52224
	ds_read_b128 v[202:205], v153 offset:53248
	ds_read_b128 v[206:209], v153 offset:54272
	ds_read_b128 v[210:213], v153 offset:55296
	ds_read_b128 v[214:217], v153 offset:56320
	s_add_i32 s34, s59, s43
	v_lshl_add_u64 v[218:219], v[218:219], 0, s[14:15]
	s_mov_b32 m0, s34
	s_nop 0
	global_load_lds_dwordx4 v[218:219], off
	s_add_i32 m0, s34, 0x2000
	s_add_u32 s30, s30, 0x100080
	v_lshl_add_u64 v[220:221], v[220:221], 0, s[14:15]
	s_addc_u32 s31, s31, 0
	s_add_i32 s34, s60, s43
	global_load_lds_dwordx4 v[220:221], off
	s_mov_b32 m0, s34
	s_nop 0
	global_load_lds_dwordx4 v130, s[30:31]
	s_add_i32 m0, s34, 0x2000
	s_nop 0
	global_load_lds_dwordx4 v134, s[30:31]
	v_lshl_add_u64 v[222:223], v[222:223], 0, s[16:17]
	s_mov_b32 m0, s49
	s_nop 0
	global_load_lds_dwordx4 v[222:223], off
	v_lshl_add_u64 v[224:225], v[224:225], 0, s[16:17]
	s_mov_b32 m0, s50
	s_nop 0
	global_load_lds_dwordx4 v[224:225], off
	s_waitcnt vmcnt(8)
	s_waitcnt lgkmcnt(0)
	s_setprio 1
	s_waitcnt lgkmcnt(0)
	v_mfma_f32_16x16x32_bf16 v[60:63], v[154:157], v[186:189], v[60:63]
	v_mfma_f32_16x16x32_bf16 v[56:59], v[162:165], v[186:189], v[56:59]
	v_mfma_f32_16x16x32_bf16 v[44:47], v[154:157], v[194:197], v[44:47]
	s_barrier
	v_mfma_f32_16x16x32_bf16 v[40:43], v[162:165], v[194:197], v[40:43]
	v_mfma_f32_16x16x32_bf16 v[28:31], v[154:157], v[202:205], v[28:31]
	v_mfma_f32_16x16x32_bf16 v[24:27], v[162:165], v[202:205], v[24:27]
	v_mfma_f32_16x16x32_bf16 v[12:15], v[154:157], v[210:213], v[12:15]
	v_mfma_f32_16x16x32_bf16 v[8:11], v[162:165], v[210:213], v[8:11]
	v_mfma_f32_16x16x32_bf16 v[60:63], v[158:161], v[190:193], v[60:63]
	v_mfma_f32_16x16x32_bf16 v[56:59], v[166:169], v[190:193], v[56:59]
	v_mfma_f32_16x16x32_bf16 v[44:47], v[158:161], v[198:201], v[44:47]
	v_mfma_f32_16x16x32_bf16 v[40:43], v[166:169], v[198:201], v[40:43]
	v_mfma_f32_16x16x32_bf16 v[28:31], v[158:161], v[206:209], v[28:31]
	v_mfma_f32_16x16x32_bf16 v[24:27], v[166:169], v[206:209], v[24:27]
	v_mfma_f32_16x16x32_bf16 v[12:15], v[158:161], v[214:217], v[12:15]
	v_mfma_f32_16x16x32_bf16 v[8:11], v[166:169], v[214:217], v[8:11]
	s_setprio 0
	s_setprio 1
	v_mfma_f32_16x16x32_bf16 v[52:55], v[170:173], v[186:189], v[52:55]
	v_mfma_f32_16x16x32_bf16 v[48:51], v[178:181], v[186:189], v[48:51]
	v_mfma_f32_16x16x32_bf16 v[36:39], v[170:173], v[194:197], v[36:39]
	v_mfma_f32_16x16x32_bf16 v[32:35], v[178:181], v[194:197], v[32:35]
	v_mfma_f32_16x16x32_bf16 v[20:23], v[170:173], v[202:205], v[20:23]
	v_mfma_f32_16x16x32_bf16 v[16:19], v[178:181], v[202:205], v[16:19]
	v_mfma_f32_16x16x32_bf16 v[4:7], v[170:173], v[210:213], v[4:7]
	v_mfma_f32_16x16x32_bf16 v[0:3], v[178:181], v[210:213], v[0:3]
	v_mfma_f32_16x16x32_bf16 v[52:55], v[174:177], v[190:193], v[52:55]
	v_mfma_f32_16x16x32_bf16 v[48:51], v[182:185], v[190:193], v[48:51]
	v_mfma_f32_16x16x32_bf16 v[36:39], v[174:177], v[198:201], v[36:39]
	v_mfma_f32_16x16x32_bf16 v[32:35], v[182:185], v[198:201], v[32:35]
	v_mfma_f32_16x16x32_bf16 v[20:23], v[174:177], v[206:209], v[20:23]
	v_mfma_f32_16x16x32_bf16 v[16:19], v[182:185], v[206:209], v[16:19]
	v_mfma_f32_16x16x32_bf16 v[4:7], v[174:177], v[214:217], v[4:7]
	v_mfma_f32_16x16x32_bf16 v[0:3], v[182:185], v[214:217], v[0:3]
	s_setprio 0
	s_barrier
	s_add_i32 s58, s58, 2
	s_add_u32 s56, s56, 0x100
	s_addc_u32 s57, s57, 0
	s_add_u32 s28, s28, 0x1000
	s_addc_u32 s29, s29, 0
	v_lshl_add_u64 v[146:147], v[146:147], 0, s[18:19]
	s_cmp_gt_u32 s58, 61
	v_lshl_add_u64 v[144:145], v[144:145], 0, s[18:19]
	s_cbranch_scc0 .LBB0_1340
	s_andn2_b64 vcc, exec, s[4:5]
	s_cbranch_vccnz .LBB0_1332
	v_mov_b32_e32 v0, 0
	s_mov_b32 s7, s20
	s_mov_b32 s6, s22
	s_mov_b64 s[8:9], s[26:27]
	s_mov_b64 s[10:11], s[24:25]
	s_mov_b32 s48, s53
	v_mov_b32_e32 v1, v0
	v_mov_b32_e32 v2, v0
	v_mov_b32_e32 v3, v0
	v_mov_b32_e32 v4, v0
	v_mov_b32_e32 v5, v0
	v_mov_b32_e32 v6, v0
	v_mov_b32_e32 v7, v0
	v_mov_b32_e32 v16, v0
	v_mov_b32_e32 v17, v0
	v_mov_b32_e32 v18, v0
	v_mov_b32_e32 v19, v0
	v_mov_b32_e32 v20, v0
	v_mov_b32_e32 v21, v0
	v_mov_b32_e32 v22, v0
	v_mov_b32_e32 v23, v0
	v_mov_b32_e32 v32, v0
	v_mov_b32_e32 v33, v0
	v_mov_b32_e32 v34, v0
	v_mov_b32_e32 v35, v0
	v_mov_b32_e32 v36, v0
	v_mov_b32_e32 v37, v0
	v_mov_b32_e32 v38, v0
	v_mov_b32_e32 v39, v0
	v_mov_b32_e32 v48, v0
	v_mov_b32_e32 v49, v0
	v_mov_b32_e32 v50, v0
	v_mov_b32_e32 v51, v0
	v_mov_b32_e32 v52, v0
	v_mov_b32_e32 v53, v0
	v_mov_b32_e32 v54, v0
	v_mov_b32_e32 v55, v0
	v_mov_b32_e32 v8, v0
	v_mov_b32_e32 v9, v0
	v_mov_b32_e32 v10, v0
	v_mov_b32_e32 v11, v0
	v_mov_b32_e32 v12, v0
	v_mov_b32_e32 v13, v0
	v_mov_b32_e32 v14, v0
	v_mov_b32_e32 v15, v0
	v_mov_b32_e32 v24, v0
	v_mov_b32_e32 v25, v0
	v_mov_b32_e32 v26, v0
	v_mov_b32_e32 v27, v0
	v_mov_b32_e32 v28, v0
	v_mov_b32_e32 v29, v0
	v_mov_b32_e32 v30, v0
	v_mov_b32_e32 v31, v0
	v_mov_b32_e32 v40, v0
	v_mov_b32_e32 v41, v0
	v_mov_b32_e32 v42, v0
	v_mov_b32_e32 v43, v0
	v_mov_b32_e32 v44, v0
	v_mov_b32_e32 v45, v0
	v_mov_b32_e32 v46, v0
	v_mov_b32_e32 v47, v0
	v_mov_b32_e32 v56, v0
	v_mov_b32_e32 v57, v0
	v_mov_b32_e32 v58, v0
	v_mov_b32_e32 v59, v0
	v_mov_b32_e32 v60, v0
	v_mov_b32_e32 v61, v0
	v_mov_b32_e32 v62, v0
	v_mov_b32_e32 v63, v0
	v_mov_b32_e32 v64, v0
	v_mov_b32_e32 v65, v0
	v_mov_b32_e32 v66, v0
	v_mov_b32_e32 v67, v0
	v_mov_b32_e32 v68, v0
	v_mov_b32_e32 v69, v0
	v_mov_b32_e32 v70, v0
	v_mov_b32_e32 v71, v0
	v_mov_b32_e32 v80, v0
	v_mov_b32_e32 v81, v0
	v_mov_b32_e32 v82, v0
	v_mov_b32_e32 v83, v0
	v_mov_b32_e32 v84, v0
	v_mov_b32_e32 v85, v0
	v_mov_b32_e32 v86, v0
	v_mov_b32_e32 v87, v0
	v_mov_b32_e32 v96, v0
	v_mov_b32_e32 v97, v0
	v_mov_b32_e32 v98, v0
	v_mov_b32_e32 v99, v0
	v_mov_b32_e32 v100, v0
	v_mov_b32_e32 v101, v0
	v_mov_b32_e32 v102, v0
	v_mov_b32_e32 v103, v0
	v_mov_b32_e32 v112, v0
	v_mov_b32_e32 v113, v0
	v_mov_b32_e32 v114, v0
	v_mov_b32_e32 v115, v0
	v_mov_b32_e32 v116, v0
	v_mov_b32_e32 v117, v0
	v_mov_b32_e32 v118, v0
	v_mov_b32_e32 v119, v0
	v_mov_b32_e32 v72, v0
	v_mov_b32_e32 v73, v0
	v_mov_b32_e32 v74, v0
	v_mov_b32_e32 v75, v0
	v_mov_b32_e32 v76, v0
	v_mov_b32_e32 v77, v0
	v_mov_b32_e32 v78, v0
	v_mov_b32_e32 v79, v0
	v_mov_b32_e32 v88, v0
	v_mov_b32_e32 v89, v0
	v_mov_b32_e32 v90, v0
	v_mov_b32_e32 v91, v0
	v_mov_b32_e32 v92, v0
	v_mov_b32_e32 v93, v0
	v_mov_b32_e32 v94, v0
	v_mov_b32_e32 v95, v0
	v_mov_b32_e32 v104, v0
	v_mov_b32_e32 v105, v0
	v_mov_b32_e32 v106, v0
	v_mov_b32_e32 v107, v0
	v_mov_b32_e32 v108, v0
	v_mov_b32_e32 v109, v0
	v_mov_b32_e32 v110, v0
	v_mov_b32_e32 v111, v0
	v_mov_b32_e32 v120, v0
	v_mov_b32_e32 v121, v0
	v_mov_b32_e32 v122, v0
	v_mov_b32_e32 v123, v0
	v_mov_b32_e32 v124, v0
	v_mov_b32_e32 v125, v0
	v_mov_b32_e32 v126, v0
	v_mov_b32_e32 v127, v0
	s_branch .LBB0_1332

.LBB0_1435:
	ds_read_b128 v[128:131], v180
	ds_read_b128 v[132:135], v180 offset:1024
	ds_read_b128 v[136:139], v180 offset:2048
	ds_read_b128 v[140:143], v180 offset:3072
	ds_read_b128 v[144:147], v181
	ds_read_b128 v[148:151], v181 offset:1024
	ds_read_b128 v[170:173], v181 offset:2048
	ds_read_b128 v[174:177], v181 offset:3072
	ds_read_b128 v[184:187], v182
	ds_read_b128 v[188:191], v182 offset:1024
	ds_read_b128 v[192:195], v182 offset:2048
	ds_read_b128 v[196:199], v182 offset:3072
	ds_read_b128 v[200:203], v182 offset:4096
	ds_read_b128 v[204:207], v182 offset:5120
	ds_read_b128 v[208:211], v182 offset:6144
	ds_read_b128 v[212:215], v182 offset:7168
	s_add_u32 s26, s24, 0xfffc0080
	s_addc_u32 s27, s25, -1
	s_cmp_eq_u32 s35, 12
	s_cselect_b32 s29, s1, s27
	s_cselect_b32 s28, s19, s26
	s_cselect_b32 s27, s17, s34
	s_cselect_b32 s26, s30, s31
	v_lshl_add_u64 v[216:217], s[24:25], 0, v[162:163]
	s_add_i32 m0, s40, 0xc000
	s_nop 0
	global_load_lds_dwordx4 v[216:217], off
	v_lshl_add_u64 v[216:217], s[24:25], 0, v[164:165]
	s_add_i32 m0, s40, 0xe000
	s_nop 0
	global_load_lds_dwordx4 v[216:217], off
	s_waitcnt vmcnt(8)
	s_waitcnt lgkmcnt(0)
	s_setprio 1
	s_waitcnt lgkmcnt(0)
	v_mfma_f32_16x16x32_bf16 v[124:127], v[128:131], v[184:187], v[124:127]
	v_mfma_f32_16x16x32_bf16 v[120:123], v[136:139], v[184:187], v[120:123]
	v_mfma_f32_16x16x32_bf16 v[108:111], v[128:131], v[192:195], v[108:111]
	s_barrier
	v_mfma_f32_16x16x32_bf16 v[104:107], v[136:139], v[192:195], v[104:107]
	v_mfma_f32_16x16x32_bf16 v[92:95], v[128:131], v[200:203], v[92:95]
	v_mfma_f32_16x16x32_bf16 v[88:91], v[136:139], v[200:203], v[88:91]
	v_mfma_f32_16x16x32_bf16 v[76:79], v[128:131], v[208:211], v[76:79]
	v_mfma_f32_16x16x32_bf16 v[72:75], v[136:139], v[208:211], v[72:75]
	v_mfma_f32_16x16x32_bf16 v[124:127], v[132:135], v[188:191], v[124:127]
	v_mfma_f32_16x16x32_bf16 v[120:123], v[140:143], v[188:191], v[120:123]
	v_mfma_f32_16x16x32_bf16 v[108:111], v[132:135], v[196:199], v[108:111]
	v_mfma_f32_16x16x32_bf16 v[104:107], v[140:143], v[196:199], v[104:107]
	v_mfma_f32_16x16x32_bf16 v[92:95], v[132:135], v[204:207], v[92:95]
	v_mfma_f32_16x16x32_bf16 v[88:91], v[140:143], v[204:207], v[88:91]
	v_mfma_f32_16x16x32_bf16 v[76:79], v[132:135], v[212:215], v[76:79]
	v_mfma_f32_16x16x32_bf16 v[72:75], v[140:143], v[212:215], v[72:75]
	s_setprio 0
	s_setprio 1
	v_mfma_f32_16x16x32_bf16 v[116:119], v[144:147], v[184:187], v[116:119]
	v_mfma_f32_16x16x32_bf16 v[112:115], v[170:173], v[184:187], v[112:115]
	v_mfma_f32_16x16x32_bf16 v[100:103], v[144:147], v[192:195], v[100:103]
	v_mfma_f32_16x16x32_bf16 v[96:99], v[170:173], v[192:195], v[96:99]
	v_mfma_f32_16x16x32_bf16 v[84:87], v[144:147], v[200:203], v[84:87]
	v_mfma_f32_16x16x32_bf16 v[80:83], v[170:173], v[200:203], v[80:83]
	v_mfma_f32_16x16x32_bf16 v[68:71], v[144:147], v[208:211], v[68:71]
	v_mfma_f32_16x16x32_bf16 v[64:67], v[170:173], v[208:211], v[64:67]
	v_mfma_f32_16x16x32_bf16 v[116:119], v[148:151], v[188:191], v[116:119]
	v_mfma_f32_16x16x32_bf16 v[112:115], v[174:177], v[188:191], v[112:115]
	v_mfma_f32_16x16x32_bf16 v[100:103], v[148:151], v[196:199], v[100:103]
	v_mfma_f32_16x16x32_bf16 v[96:99], v[174:177], v[196:199], v[96:99]
	v_mfma_f32_16x16x32_bf16 v[84:87], v[148:151], v[204:207], v[84:87]
	v_mfma_f32_16x16x32_bf16 v[80:83], v[174:177], v[204:207], v[80:83]
	v_mfma_f32_16x16x32_bf16 v[68:71], v[148:151], v[212:215], v[68:71]
	v_mfma_f32_16x16x32_bf16 v[64:67], v[174:177], v[212:215], v[64:67]
	s_setprio 0
	s_barrier
	ds_read_b128 v[184:187], v182 offset:16384
	ds_read_b128 v[188:191], v182 offset:17408
	ds_read_b128 v[192:195], v182 offset:18432
	ds_read_b128 v[196:199], v182 offset:19456
	ds_read_b128 v[200:203], v182 offset:20480
	ds_read_b128 v[204:207], v182 offset:21504
	ds_read_b128 v[208:211], v182 offset:22528
	ds_read_b128 v[212:215], v182 offset:23552
	s_add_i32 s54, s50, s39
	v_lshl_add_u64 v[216:217], s[26:27], 0, v[154:155]
	s_mov_b32 m0, s54
	v_lshl_add_u64 v[218:219], s[26:27], 0, v[158:159]
	global_load_lds_dwordx4 v[216:217], off
	s_add_i32 m0, s54, 0x2000
	s_add_u32 s54, s26, 0x100000
	s_addc_u32 s55, s27, 0
	s_add_i32 s56, s51, s39
	global_load_lds_dwordx4 v[218:219], off
	s_mov_b32 m0, s56
	v_lshl_add_u64 v[220:221], s[28:29], 0, v[152:153]
	global_load_lds_dwordx4 v154, s[54:55]
	s_add_i32 m0, s56, 0x2000
	v_lshl_add_u64 v[222:223], s[28:29], 0, v[156:157]
	global_load_lds_dwordx4 v158, s[54:55]
	s_mov_b32 m0, s40
	s_nop 0
	global_load_lds_dwordx4 v[220:221], off
	s_mov_b32 m0, s41
	s_nop 0
	global_load_lds_dwordx4 v[222:223], off
	s_waitcnt vmcnt(8)
	s_waitcnt lgkmcnt(0)
	s_setprio 1
	s_waitcnt lgkmcnt(0)
	v_mfma_f32_16x16x32_bf16 v[60:63], v[128:131], v[184:187], v[60:63]
	v_mfma_f32_16x16x32_bf16 v[56:59], v[136:139], v[184:187], v[56:59]
	v_mfma_f32_16x16x32_bf16 v[44:47], v[128:131], v[192:195], v[44:47]
	s_barrier
	v_mfma_f32_16x16x32_bf16 v[40:43], v[136:139], v[192:195], v[40:43]
	v_mfma_f32_16x16x32_bf16 v[28:31], v[128:131], v[200:203], v[28:31]
	v_mfma_f32_16x16x32_bf16 v[24:27], v[136:139], v[200:203], v[24:27]
	v_mfma_f32_16x16x32_bf16 v[12:15], v[128:131], v[208:211], v[12:15]
	v_mfma_f32_16x16x32_bf16 v[8:11], v[136:139], v[208:211], v[8:11]
	v_mfma_f32_16x16x32_bf16 v[60:63], v[132:135], v[188:191], v[60:63]
	v_mfma_f32_16x16x32_bf16 v[56:59], v[140:143], v[188:191], v[56:59]
	v_mfma_f32_16x16x32_bf16 v[44:47], v[132:135], v[196:199], v[44:47]
	v_mfma_f32_16x16x32_bf16 v[40:43], v[140:143], v[196:199], v[40:43]
	v_mfma_f32_16x16x32_bf16 v[28:31], v[132:135], v[204:207], v[28:31]
	v_mfma_f32_16x16x32_bf16 v[24:27], v[140:143], v[204:207], v[24:27]
	v_mfma_f32_16x16x32_bf16 v[12:15], v[132:135], v[212:215], v[12:15]
	v_mfma_f32_16x16x32_bf16 v[8:11], v[140:143], v[212:215], v[8:11]
	s_setprio 0
	s_setprio 1
	v_mfma_f32_16x16x32_bf16 v[52:55], v[144:147], v[184:187], v[52:55]
	v_mfma_f32_16x16x32_bf16 v[48:51], v[170:173], v[184:187], v[48:51]
	v_mfma_f32_16x16x32_bf16 v[36:39], v[144:147], v[192:195], v[36:39]
	v_mfma_f32_16x16x32_bf16 v[32:35], v[170:173], v[192:195], v[32:35]
	v_mfma_f32_16x16x32_bf16 v[20:23], v[144:147], v[200:203], v[20:23]
	v_mfma_f32_16x16x32_bf16 v[16:19], v[170:173], v[200:203], v[16:19]
	v_mfma_f32_16x16x32_bf16 v[4:7], v[144:147], v[208:211], v[4:7]
	v_mfma_f32_16x16x32_bf16 v[0:3], v[170:173], v[208:211], v[0:3]
	v_mfma_f32_16x16x32_bf16 v[52:55], v[148:151], v[188:191], v[52:55]
	v_mfma_f32_16x16x32_bf16 v[48:51], v[174:177], v[188:191], v[48:51]
	v_mfma_f32_16x16x32_bf16 v[36:39], v[148:151], v[196:199], v[36:39]
	v_mfma_f32_16x16x32_bf16 v[32:35], v[174:177], v[196:199], v[32:35]
	v_mfma_f32_16x16x32_bf16 v[20:23], v[148:151], v[204:207], v[20:23]
	v_mfma_f32_16x16x32_bf16 v[16:19], v[174:177], v[204:207], v[16:19]
	v_mfma_f32_16x16x32_bf16 v[4:7], v[148:151], v[212:215], v[4:7]
	v_mfma_f32_16x16x32_bf16 v[0:3], v[174:177], v[212:215], v[0:3]
	s_setprio 0
	s_barrier
	s_add_i32 s54, 0, 0x18000
	s_add_i32 s55, 0, 0x1c000
	v_add_u32_e32 v140, s54, v178
	v_add_u32_e32 v174, s55, v178
	ds_read_b128 v[128:131], v140
	ds_read_b128 v[132:135], v140 offset:1024
	ds_read_b128 v[136:139], v140 offset:2048
	ds_read_b128 v[140:143], v140 offset:3072
	ds_read_b128 v[144:147], v174
	ds_read_b128 v[148:151], v174 offset:1024
	ds_read_b128 v[170:173], v174 offset:2048
	ds_read_b128 v[174:177], v174 offset:3072
	ds_read_b128 v[184:187], v182 offset:32768
	ds_read_b128 v[188:191], v182 offset:33792
	ds_read_b128 v[192:195], v182 offset:34816
	ds_read_b128 v[196:199], v182 offset:35840
	ds_read_b128 v[200:203], v182 offset:36864
	ds_read_b128 v[204:207], v182 offset:37888
	ds_read_b128 v[208:211], v182 offset:38912
	ds_read_b128 v[212:215], v182 offset:39936
	s_add_u32 s28, s28, 0x40000
	s_addc_u32 s29, s29, 0
	s_mov_b32 m0, s42
	s_nop 0
	global_load_lds_dwordx4 v152, s[28:29]
	s_mov_b32 m0, s43
	s_nop 0
	global_load_lds_dwordx4 v156, s[28:29]
	s_waitcnt vmcnt(8)
	s_waitcnt lgkmcnt(0)
	s_setprio 1
	s_waitcnt lgkmcnt(0)
	v_mfma_f32_16x16x32_bf16 v[124:127], v[128:131], v[184:187], v[124:127]
	v_mfma_f32_16x16x32_bf16 v[120:123], v[136:139], v[184:187], v[120:123]
	v_mfma_f32_16x16x32_bf16 v[108:111], v[128:131], v[192:195], v[108:111]
	s_barrier
	v_mfma_f32_16x16x32_bf16 v[104:107], v[136:139], v[192:195], v[104:107]
	v_mfma_f32_16x16x32_bf16 v[92:95], v[128:131], v[200:203], v[92:95]
	v_mfma_f32_16x16x32_bf16 v[88:91], v[136:139], v[200:203], v[88:91]
	v_mfma_f32_16x16x32_bf16 v[76:79], v[128:131], v[208:211], v[76:79]
	v_mfma_f32_16x16x32_bf16 v[72:75], v[136:139], v[208:211], v[72:75]
	v_mfma_f32_16x16x32_bf16 v[124:127], v[132:135], v[188:191], v[124:127]
	v_mfma_f32_16x16x32_bf16 v[120:123], v[140:143], v[188:191], v[120:123]
	v_mfma_f32_16x16x32_bf16 v[108:111], v[132:135], v[196:199], v[108:111]
	v_mfma_f32_16x16x32_bf16 v[104:107], v[140:143], v[196:199], v[104:107]
	v_mfma_f32_16x16x32_bf16 v[92:95], v[132:135], v[204:207], v[92:95]
	v_mfma_f32_16x16x32_bf16 v[88:91], v[140:143], v[204:207], v[88:91]
	v_mfma_f32_16x16x32_bf16 v[76:79], v[132:135], v[212:215], v[76:79]
	v_mfma_f32_16x16x32_bf16 v[72:75], v[140:143], v[212:215], v[72:75]
	s_setprio 0
	s_setprio 1
	v_mfma_f32_16x16x32_bf16 v[116:119], v[144:147], v[184:187], v[116:119]
	v_mfma_f32_16x16x32_bf16 v[112:115], v[170:173], v[184:187], v[112:115]
	v_mfma_f32_16x16x32_bf16 v[100:103], v[144:147], v[192:195], v[100:103]
	v_mfma_f32_16x16x32_bf16 v[96:99], v[170:173], v[192:195], v[96:99]
	v_mfma_f32_16x16x32_bf16 v[84:87], v[144:147], v[200:203], v[84:87]
	v_mfma_f32_16x16x32_bf16 v[80:83], v[170:173], v[200:203], v[80:83]
	v_mfma_f32_16x16x32_bf16 v[68:71], v[144:147], v[208:211], v[68:71]
	v_mfma_f32_16x16x32_bf16 v[64:67], v[170:173], v[208:211], v[64:67]
	v_mfma_f32_16x16x32_bf16 v[116:119], v[148:151], v[188:191], v[116:119]
	v_mfma_f32_16x16x32_bf16 v[112:115], v[174:177], v[188:191], v[112:115]
	v_mfma_f32_16x16x32_bf16 v[100:103], v[148:151], v[196:199], v[100:103]
	v_mfma_f32_16x16x32_bf16 v[96:99], v[174:177], v[196:199], v[96:99]
	v_mfma_f32_16x16x32_bf16 v[84:87], v[148:151], v[204:207], v[84:87]
	v_mfma_f32_16x16x32_bf16 v[80:83], v[174:177], v[204:207], v[80:83]
	v_mfma_f32_16x16x32_bf16 v[68:71], v[148:151], v[212:215], v[68:71]
	v_mfma_f32_16x16x32_bf16 v[64:67], v[174:177], v[212:215], v[64:67]
	s_setprio 0
	s_barrier
	ds_read_b128 v[184:187], v182 offset:49152
	ds_read_b128 v[188:191], v182 offset:50176
	ds_read_b128 v[192:195], v182 offset:51200
	ds_read_b128 v[196:199], v182 offset:52224
	ds_read_b128 v[200:203], v182 offset:53248
	ds_read_b128 v[204:207], v182 offset:54272
	ds_read_b128 v[208:211], v182 offset:55296
	ds_read_b128 v[212:215], v182 offset:56320
	s_add_i32 s28, s54, s39
	v_lshl_add_u64 v[216:217], v[216:217], 0, s[14:15]
	s_mov_b32 m0, s28
	s_nop 0
	global_load_lds_dwordx4 v[216:217], off
	s_add_i32 m0, s28, 0x2000
	s_add_u32 s26, s26, 0x100080
	v_lshl_add_u64 v[218:219], v[218:219], 0, s[14:15]
	s_addc_u32 s27, s27, 0
	s_add_i32 s28, s55, s39
	global_load_lds_dwordx4 v[218:219], off
	s_mov_b32 m0, s28
	s_nop 0
	global_load_lds_dwordx4 v154, s[26:27]
	s_add_i32 m0, s28, 0x2000
	s_nop 0
	global_load_lds_dwordx4 v158, s[26:27]
	v_lshl_add_u64 v[220:221], v[220:221], 0, s[14:15]
	s_mov_b32 m0, s45
	s_nop 0
	global_load_lds_dwordx4 v[220:221], off
	v_lshl_add_u64 v[222:223], v[222:223], 0, s[14:15]
	s_mov_b32 m0, s46
	s_nop 0
	global_load_lds_dwordx4 v[222:223], off
	s_waitcnt vmcnt(8)
	s_waitcnt lgkmcnt(0)
	s_setprio 1
	s_waitcnt lgkmcnt(0)
	v_mfma_f32_16x16x32_bf16 v[60:63], v[128:131], v[184:187], v[60:63]
	v_mfma_f32_16x16x32_bf16 v[56:59], v[136:139], v[184:187], v[56:59]
	v_mfma_f32_16x16x32_bf16 v[44:47], v[128:131], v[192:195], v[44:47]
	s_barrier
	v_mfma_f32_16x16x32_bf16 v[40:43], v[136:139], v[192:195], v[40:43]
	v_mfma_f32_16x16x32_bf16 v[28:31], v[128:131], v[200:203], v[28:31]
	v_mfma_f32_16x16x32_bf16 v[24:27], v[136:139], v[200:203], v[24:27]
	v_mfma_f32_16x16x32_bf16 v[12:15], v[128:131], v[208:211], v[12:15]
	v_mfma_f32_16x16x32_bf16 v[8:11], v[136:139], v[208:211], v[8:11]
	v_mfma_f32_16x16x32_bf16 v[60:63], v[132:135], v[188:191], v[60:63]
	v_mfma_f32_16x16x32_bf16 v[56:59], v[140:143], v[188:191], v[56:59]
	v_mfma_f32_16x16x32_bf16 v[44:47], v[132:135], v[196:199], v[44:47]
	v_mfma_f32_16x16x32_bf16 v[40:43], v[140:143], v[196:199], v[40:43]
	v_mfma_f32_16x16x32_bf16 v[28:31], v[132:135], v[204:207], v[28:31]
	v_mfma_f32_16x16x32_bf16 v[24:27], v[140:143], v[204:207], v[24:27]
	v_mfma_f32_16x16x32_bf16 v[12:15], v[132:135], v[212:215], v[12:15]
	v_mfma_f32_16x16x32_bf16 v[8:11], v[140:143], v[212:215], v[8:11]
	s_setprio 0
	s_setprio 1
	v_mfma_f32_16x16x32_bf16 v[52:55], v[144:147], v[184:187], v[52:55]
	v_mfma_f32_16x16x32_bf16 v[48:51], v[170:173], v[184:187], v[48:51]
	v_mfma_f32_16x16x32_bf16 v[36:39], v[144:147], v[192:195], v[36:39]
	v_mfma_f32_16x16x32_bf16 v[32:35], v[170:173], v[192:195], v[32:35]
	v_mfma_f32_16x16x32_bf16 v[20:23], v[144:147], v[200:203], v[20:23]
	v_mfma_f32_16x16x32_bf16 v[16:19], v[170:173], v[200:203], v[16:19]
	v_mfma_f32_16x16x32_bf16 v[4:7], v[144:147], v[208:211], v[4:7]
	v_mfma_f32_16x16x32_bf16 v[0:3], v[170:173], v[208:211], v[0:3]
	v_mfma_f32_16x16x32_bf16 v[52:55], v[148:151], v[188:191], v[52:55]
	v_mfma_f32_16x16x32_bf16 v[48:51], v[174:177], v[188:191], v[48:51]
	v_mfma_f32_16x16x32_bf16 v[36:39], v[148:151], v[196:199], v[36:39]
	v_mfma_f32_16x16x32_bf16 v[32:35], v[174:177], v[196:199], v[32:35]
	v_mfma_f32_16x16x32_bf16 v[20:23], v[148:151], v[204:207], v[20:23]
	v_mfma_f32_16x16x32_bf16 v[16:19], v[174:177], v[204:207], v[16:19]
	v_mfma_f32_16x16x32_bf16 v[4:7], v[148:151], v[212:215], v[4:7]
	v_mfma_f32_16x16x32_bf16 v[0:3], v[174:177], v[212:215], v[0:3]
	s_setprio 0
	s_barrier
	s_add_i32 s35, s35, 2
	s_add_u32 s24, s24, 0x100
	s_addc_u32 s25, s25, 0
	s_add_u32 s31, s31, 0x100
	s_addc_u32 s34, s34, 0
	s_cmp_gt_u32 s35, 13
	s_cbranch_scc0 .LBB0_1435
	s_and_b64 vcc, exec, s[8:9]
	s_cbranch_vccz .LBB0_1438
	s_barrier

.LBB0_1543:
	ds_read_b128 v[128:131], v167
	ds_read_b128 v[154:157], v167 offset:1024
	ds_read_b128 v[172:175], v167 offset:2048
	ds_read_b128 v[176:179], v167 offset:3072
	ds_read_b128 v[180:183], v168
	ds_read_b128 v[184:187], v168 offset:1024
	ds_read_b128 v[188:191], v168 offset:2048
	ds_read_b128 v[192:195], v168 offset:3072
	ds_read_b128 v[196:199], v169
	ds_read_b128 v[200:203], v169 offset:1024
	ds_read_b128 v[204:207], v169 offset:2048
	ds_read_b128 v[208:211], v169 offset:3072
	ds_read_b128 v[212:215], v169 offset:4096
	ds_read_b128 v[216:219], v169 offset:5120
	ds_read_b128 v[220:223], v169 offset:6144
	ds_read_b128 v[224:227], v169 offset:7168
	s_add_u32 s22, s20, 0x1000
	s_addc_u32 s23, s21, 0
	s_cmp_eq_u32 s54, 60
	s_cselect_b32 s27, s13, s23
	s_cselect_b32 s26, s50, s22
	s_cselect_b32 s25, s11, s53
	s_cselect_b32 s24, s51, s52
	v_lshl_add_u64 v[160:161], s[20:21], 0, v[144:145]
	s_add_i32 m0, s19, 0xc000
	s_nop 0
	global_load_lds_dwordx4 v[160:161], off
	v_lshl_add_u64 v[160:161], s[20:21], 0, v[146:147]
	s_add_i32 m0, s19, 0xe000
	s_nop 0
	global_load_lds_dwordx4 v[160:161], off
	s_waitcnt vmcnt(8)
	s_waitcnt lgkmcnt(0)
	s_setprio 1
	s_waitcnt lgkmcnt(0)
	v_mfma_f32_16x16x32_bf16 v[124:127], v[128:131], v[196:199], v[124:127]
	v_mfma_f32_16x16x32_bf16 v[120:123], v[172:175], v[196:199], v[120:123]
	v_mfma_f32_16x16x32_bf16 v[108:111], v[128:131], v[204:207], v[108:111]
	s_barrier
	v_mfma_f32_16x16x32_bf16 v[104:107], v[172:175], v[204:207], v[104:107]
	v_mfma_f32_16x16x32_bf16 v[92:95], v[128:131], v[212:215], v[92:95]
	v_mfma_f32_16x16x32_bf16 v[88:91], v[172:175], v[212:215], v[88:91]
	v_mfma_f32_16x16x32_bf16 v[76:79], v[128:131], v[220:223], v[76:79]
	v_mfma_f32_16x16x32_bf16 v[72:75], v[172:175], v[220:223], v[72:75]
	v_mfma_f32_16x16x32_bf16 v[124:127], v[154:157], v[200:203], v[124:127]
	v_mfma_f32_16x16x32_bf16 v[120:123], v[176:179], v[200:203], v[120:123]
	v_mfma_f32_16x16x32_bf16 v[108:111], v[154:157], v[208:211], v[108:111]
	v_mfma_f32_16x16x32_bf16 v[104:107], v[176:179], v[208:211], v[104:107]
	v_mfma_f32_16x16x32_bf16 v[92:95], v[154:157], v[216:219], v[92:95]
	v_mfma_f32_16x16x32_bf16 v[88:91], v[176:179], v[216:219], v[88:91]
	v_mfma_f32_16x16x32_bf16 v[76:79], v[154:157], v[224:227], v[76:79]
	v_mfma_f32_16x16x32_bf16 v[72:75], v[176:179], v[224:227], v[72:75]
	s_setprio 0
	s_setprio 1
	v_mfma_f32_16x16x32_bf16 v[116:119], v[180:183], v[196:199], v[116:119]
	v_mfma_f32_16x16x32_bf16 v[112:115], v[188:191], v[196:199], v[112:115]
	v_mfma_f32_16x16x32_bf16 v[100:103], v[180:183], v[204:207], v[100:103]
	v_mfma_f32_16x16x32_bf16 v[96:99], v[188:191], v[204:207], v[96:99]
	v_mfma_f32_16x16x32_bf16 v[84:87], v[180:183], v[212:215], v[84:87]
	v_mfma_f32_16x16x32_bf16 v[80:83], v[188:191], v[212:215], v[80:83]
	v_mfma_f32_16x16x32_bf16 v[68:71], v[180:183], v[220:223], v[68:71]
	v_mfma_f32_16x16x32_bf16 v[64:67], v[188:191], v[220:223], v[64:67]
	v_mfma_f32_16x16x32_bf16 v[116:119], v[184:187], v[200:203], v[116:119]
	v_mfma_f32_16x16x32_bf16 v[112:115], v[192:195], v[200:203], v[112:115]
	v_mfma_f32_16x16x32_bf16 v[100:103], v[184:187], v[208:211], v[100:103]
	v_mfma_f32_16x16x32_bf16 v[96:99], v[192:195], v[208:211], v[96:99]
	v_mfma_f32_16x16x32_bf16 v[84:87], v[184:187], v[216:219], v[84:87]
	v_mfma_f32_16x16x32_bf16 v[80:83], v[192:195], v[216:219], v[80:83]
	v_mfma_f32_16x16x32_bf16 v[68:71], v[184:187], v[224:227], v[68:71]
	v_mfma_f32_16x16x32_bf16 v[64:67], v[192:195], v[224:227], v[64:67]
	s_setprio 0
	s_barrier
	ds_read_b128 v[196:199], v169 offset:16384
	ds_read_b128 v[200:203], v169 offset:17408
	ds_read_b128 v[204:207], v169 offset:18432
	ds_read_b128 v[208:211], v169 offset:19456
	ds_read_b128 v[212:215], v169 offset:20480
	ds_read_b128 v[216:219], v169 offset:21504
	ds_read_b128 v[220:223], v169 offset:22528
	ds_read_b128 v[224:227], v169 offset:23552
	s_add_i32 s20, s45, s30
	v_lshl_add_u64 v[160:161], s[24:25], 0, v[134:135]
	s_mov_b32 m0, s20
	v_lshl_add_u64 v[164:165], s[24:25], 0, v[138:139]
	global_load_lds_dwordx4 v[160:161], off
	s_add_i32 m0, s20, 0x2000
	s_add_u32 s20, s24, 0x100000
	s_addc_u32 s21, s25, 0
	s_add_i32 s55, s46, s30
	global_load_lds_dwordx4 v[164:165], off
	s_mov_b32 m0, s55
	v_lshl_add_u64 v[228:229], s[26:27], 0, v[132:133]
	global_load_lds_dwordx4 v134, s[20:21]
	s_add_i32 m0, s55, 0x2000
	v_lshl_add_u64 v[230:231], s[26:27], 0, v[136:137]
	global_load_lds_dwordx4 v138, s[20:21]
	s_mov_b32 m0, s19
	s_nop 0
	global_load_lds_dwordx4 v[228:229], off
	s_mov_b32 m0, s36
	s_nop 0
	global_load_lds_dwordx4 v[230:231], off
	s_waitcnt vmcnt(8)
	s_waitcnt lgkmcnt(0)
	s_setprio 1
	s_waitcnt lgkmcnt(0)
	v_mfma_f32_16x16x32_bf16 v[60:63], v[128:131], v[196:199], v[60:63]
	v_mfma_f32_16x16x32_bf16 v[56:59], v[172:175], v[196:199], v[56:59]
	v_mfma_f32_16x16x32_bf16 v[44:47], v[128:131], v[204:207], v[44:47]
	s_barrier
	v_mfma_f32_16x16x32_bf16 v[40:43], v[172:175], v[204:207], v[40:43]
	v_mfma_f32_16x16x32_bf16 v[28:31], v[128:131], v[212:215], v[28:31]
	v_mfma_f32_16x16x32_bf16 v[24:27], v[172:175], v[212:215], v[24:27]
	v_mfma_f32_16x16x32_bf16 v[12:15], v[128:131], v[220:223], v[12:15]
	v_mfma_f32_16x16x32_bf16 v[8:11], v[172:175], v[220:223], v[8:11]
	v_mfma_f32_16x16x32_bf16 v[60:63], v[154:157], v[200:203], v[60:63]
	v_mfma_f32_16x16x32_bf16 v[56:59], v[176:179], v[200:203], v[56:59]
	v_mfma_f32_16x16x32_bf16 v[44:47], v[154:157], v[208:211], v[44:47]
	v_mfma_f32_16x16x32_bf16 v[40:43], v[176:179], v[208:211], v[40:43]
	v_mfma_f32_16x16x32_bf16 v[28:31], v[154:157], v[216:219], v[28:31]
	v_mfma_f32_16x16x32_bf16 v[24:27], v[176:179], v[216:219], v[24:27]
	v_mfma_f32_16x16x32_bf16 v[12:15], v[154:157], v[224:227], v[12:15]
	v_mfma_f32_16x16x32_bf16 v[8:11], v[176:179], v[224:227], v[8:11]
	s_setprio 0
	s_setprio 1
	v_mfma_f32_16x16x32_bf16 v[52:55], v[180:183], v[196:199], v[52:55]
	v_mfma_f32_16x16x32_bf16 v[48:51], v[188:191], v[196:199], v[48:51]
	v_mfma_f32_16x16x32_bf16 v[36:39], v[180:183], v[204:207], v[36:39]
	v_mfma_f32_16x16x32_bf16 v[32:35], v[188:191], v[204:207], v[32:35]
	v_mfma_f32_16x16x32_bf16 v[20:23], v[180:183], v[212:215], v[20:23]
	v_mfma_f32_16x16x32_bf16 v[16:19], v[188:191], v[212:215], v[16:19]
	v_mfma_f32_16x16x32_bf16 v[4:7], v[180:183], v[220:223], v[4:7]
	v_mfma_f32_16x16x32_bf16 v[0:3], v[188:191], v[220:223], v[0:3]
	v_mfma_f32_16x16x32_bf16 v[52:55], v[184:187], v[200:203], v[52:55]
	v_mfma_f32_16x16x32_bf16 v[48:51], v[192:195], v[200:203], v[48:51]
	v_mfma_f32_16x16x32_bf16 v[36:39], v[184:187], v[208:211], v[36:39]
	v_mfma_f32_16x16x32_bf16 v[32:35], v[192:195], v[208:211], v[32:35]
	v_mfma_f32_16x16x32_bf16 v[20:23], v[184:187], v[216:219], v[20:23]
	v_mfma_f32_16x16x32_bf16 v[16:19], v[192:195], v[216:219], v[16:19]
	v_mfma_f32_16x16x32_bf16 v[4:7], v[184:187], v[224:227], v[4:7]
	v_mfma_f32_16x16x32_bf16 v[0:3], v[192:195], v[224:227], v[0:3]
	s_setprio 0
	s_barrier
	s_add_i32 s55, 0, 0x18000
	v_add_u32_e32 v153, s55, v159
	s_add_i32 s56, 0, 0x1c000
	ds_read_b128 v[128:131], v153
	ds_read_b128 v[154:157], v153 offset:1024
	ds_read_b128 v[172:175], v153 offset:2048
	ds_read_b128 v[176:179], v153 offset:3072
	v_add_u32_e32 v153, s56, v159
	ds_read_b128 v[180:183], v153
	ds_read_b128 v[184:187], v153 offset:1024
	ds_read_b128 v[188:191], v153 offset:2048
	ds_read_b128 v[192:195], v153 offset:3072
	ds_read_b128 v[196:199], v169 offset:32768
	ds_read_b128 v[200:203], v169 offset:33792
	ds_read_b128 v[204:207], v169 offset:34816
	ds_read_b128 v[208:211], v169 offset:35840
	ds_read_b128 v[212:215], v169 offset:36864
	ds_read_b128 v[216:219], v169 offset:37888
	ds_read_b128 v[220:223], v169 offset:38912
	ds_read_b128 v[224:227], v169 offset:39936
	s_add_u32 s20, s26, 0x100000
	s_addc_u32 s21, s27, 0
	s_mov_b32 m0, s37
	s_nop 0
	global_load_lds_dwordx4 v132, s[20:21]
	s_mov_b32 m0, s38
	s_nop 0
	global_load_lds_dwordx4 v136, s[20:21]
	s_waitcnt vmcnt(8)
	s_waitcnt lgkmcnt(0)
	s_setprio 1
	s_waitcnt lgkmcnt(0)
	v_mfma_f32_16x16x32_bf16 v[124:127], v[128:131], v[196:199], v[124:127]
	v_mfma_f32_16x16x32_bf16 v[120:123], v[172:175], v[196:199], v[120:123]
	v_mfma_f32_16x16x32_bf16 v[108:111], v[128:131], v[204:207], v[108:111]
	s_barrier
	v_mfma_f32_16x16x32_bf16 v[104:107], v[172:175], v[204:207], v[104:107]
	v_mfma_f32_16x16x32_bf16 v[92:95], v[128:131], v[212:215], v[92:95]
	v_mfma_f32_16x16x32_bf16 v[88:91], v[172:175], v[212:215], v[88:91]
	v_mfma_f32_16x16x32_bf16 v[76:79], v[128:131], v[220:223], v[76:79]
	v_mfma_f32_16x16x32_bf16 v[72:75], v[172:175], v[220:223], v[72:75]
	v_mfma_f32_16x16x32_bf16 v[124:127], v[154:157], v[200:203], v[124:127]
	v_mfma_f32_16x16x32_bf16 v[120:123], v[176:179], v[200:203], v[120:123]
	v_mfma_f32_16x16x32_bf16 v[108:111], v[154:157], v[208:211], v[108:111]
	v_mfma_f32_16x16x32_bf16 v[104:107], v[176:179], v[208:211], v[104:107]
	v_mfma_f32_16x16x32_bf16 v[92:95], v[154:157], v[216:219], v[92:95]
	v_mfma_f32_16x16x32_bf16 v[88:91], v[176:179], v[216:219], v[88:91]
	v_mfma_f32_16x16x32_bf16 v[76:79], v[154:157], v[224:227], v[76:79]
	v_mfma_f32_16x16x32_bf16 v[72:75], v[176:179], v[224:227], v[72:75]
	s_setprio 0
	s_setprio 1
	v_mfma_f32_16x16x32_bf16 v[116:119], v[180:183], v[196:199], v[116:119]
	v_mfma_f32_16x16x32_bf16 v[112:115], v[188:191], v[196:199], v[112:115]
	v_mfma_f32_16x16x32_bf16 v[100:103], v[180:183], v[204:207], v[100:103]
	v_mfma_f32_16x16x32_bf16 v[96:99], v[188:191], v[204:207], v[96:99]
	v_mfma_f32_16x16x32_bf16 v[84:87], v[180:183], v[212:215], v[84:87]
	v_mfma_f32_16x16x32_bf16 v[80:83], v[188:191], v[212:215], v[80:83]
	v_mfma_f32_16x16x32_bf16 v[68:71], v[180:183], v[220:223], v[68:71]
	v_mfma_f32_16x16x32_bf16 v[64:67], v[188:191], v[220:223], v[64:67]
	v_mfma_f32_16x16x32_bf16 v[116:119], v[184:187], v[200:203], v[116:119]
	v_mfma_f32_16x16x32_bf16 v[112:115], v[192:195], v[200:203], v[112:115]
	v_mfma_f32_16x16x32_bf16 v[100:103], v[184:187], v[208:211], v[100:103]
	v_mfma_f32_16x16x32_bf16 v[96:99], v[192:195], v[208:211], v[96:99]
	v_mfma_f32_16x16x32_bf16 v[84:87], v[184:187], v[216:219], v[84:87]
	v_mfma_f32_16x16x32_bf16 v[80:83], v[192:195], v[216:219], v[80:83]
	v_mfma_f32_16x16x32_bf16 v[68:71], v[184:187], v[224:227], v[68:71]
	v_mfma_f32_16x16x32_bf16 v[64:67], v[192:195], v[224:227], v[64:67]
	s_setprio 0
	s_barrier
	ds_read_b128 v[196:199], v169 offset:49152
	ds_read_b128 v[200:203], v169 offset:50176
	ds_read_b128 v[204:207], v169 offset:51200
	ds_read_b128 v[208:211], v169 offset:52224
	ds_read_b128 v[212:215], v169 offset:53248
	ds_read_b128 v[216:219], v169 offset:54272
	ds_read_b128 v[220:223], v169 offset:55296
	ds_read_b128 v[224:227], v169 offset:56320
	s_add_i32 s20, s55, s30
	v_lshl_add_u64 v[160:161], v[160:161], 0, s[8:9]
	s_mov_b32 m0, s20
	s_nop 0
	global_load_lds_dwordx4 v[160:161], off
	s_add_i32 m0, s20, 0x2000
	s_add_u32 s20, s24, 0x100800
	v_lshl_add_u64 v[160:161], v[164:165], 0, s[8:9]
	s_addc_u32 s21, s25, 0
	s_add_i32 s24, s56, s30
	global_load_lds_dwordx4 v[160:161], off
	v_lshl_add_u64 v[160:161], s[20:21], 0, v[134:135]
	s_mov_b32 m0, s24
	s_nop 0
	global_load_lds_dwordx4 v[160:161], off
	v_lshl_add_u64 v[160:161], s[20:21], 0, v[138:139]
	s_add_i32 m0, s24, 0x2000
	s_nop 0
	global_load_lds_dwordx4 v[160:161], off
	v_lshl_add_u64 v[160:161], v[228:229], 0, s[8:9]
	s_mov_b32 m0, s41
	s_nop 0
	global_load_lds_dwordx4 v[160:161], off
	v_lshl_add_u64 v[160:161], v[230:231], 0, s[8:9]
	s_mov_b32 m0, s42
	s_nop 0
	global_load_lds_dwordx4 v[160:161], off
	s_waitcnt vmcnt(8)
	s_waitcnt lgkmcnt(0)
	s_setprio 1
	s_waitcnt lgkmcnt(0)
	v_mfma_f32_16x16x32_bf16 v[60:63], v[128:131], v[196:199], v[60:63]
	v_mfma_f32_16x16x32_bf16 v[56:59], v[172:175], v[196:199], v[56:59]
	v_mfma_f32_16x16x32_bf16 v[44:47], v[128:131], v[204:207], v[44:47]
	s_barrier
	v_mfma_f32_16x16x32_bf16 v[40:43], v[172:175], v[204:207], v[40:43]
	v_mfma_f32_16x16x32_bf16 v[28:31], v[128:131], v[212:215], v[28:31]
	v_mfma_f32_16x16x32_bf16 v[24:27], v[172:175], v[212:215], v[24:27]
	v_mfma_f32_16x16x32_bf16 v[12:15], v[128:131], v[220:223], v[12:15]
	v_mfma_f32_16x16x32_bf16 v[8:11], v[172:175], v[220:223], v[8:11]
	v_mfma_f32_16x16x32_bf16 v[60:63], v[154:157], v[200:203], v[60:63]
	v_mfma_f32_16x16x32_bf16 v[56:59], v[176:179], v[200:203], v[56:59]
	v_mfma_f32_16x16x32_bf16 v[44:47], v[154:157], v[208:211], v[44:47]
	v_mfma_f32_16x16x32_bf16 v[40:43], v[176:179], v[208:211], v[40:43]
	v_mfma_f32_16x16x32_bf16 v[28:31], v[154:157], v[216:219], v[28:31]
	v_mfma_f32_16x16x32_bf16 v[24:27], v[176:179], v[216:219], v[24:27]
	v_mfma_f32_16x16x32_bf16 v[12:15], v[154:157], v[224:227], v[12:15]
	v_mfma_f32_16x16x32_bf16 v[8:11], v[176:179], v[224:227], v[8:11]
	s_setprio 0
	s_setprio 1
	v_mfma_f32_16x16x32_bf16 v[52:55], v[180:183], v[196:199], v[52:55]
	v_mfma_f32_16x16x32_bf16 v[48:51], v[188:191], v[196:199], v[48:51]
	v_mfma_f32_16x16x32_bf16 v[36:39], v[180:183], v[204:207], v[36:39]
	v_mfma_f32_16x16x32_bf16 v[32:35], v[188:191], v[204:207], v[32:35]
	v_mfma_f32_16x16x32_bf16 v[20:23], v[180:183], v[212:215], v[20:23]
	v_mfma_f32_16x16x32_bf16 v[16:19], v[188:191], v[212:215], v[16:19]
	v_mfma_f32_16x16x32_bf16 v[4:7], v[180:183], v[220:223], v[4:7]
	v_mfma_f32_16x16x32_bf16 v[0:3], v[188:191], v[220:223], v[0:3]
	v_mfma_f32_16x16x32_bf16 v[52:55], v[184:187], v[200:203], v[52:55]
	v_mfma_f32_16x16x32_bf16 v[48:51], v[192:195], v[200:203], v[48:51]
	v_mfma_f32_16x16x32_bf16 v[36:39], v[184:187], v[208:211], v[36:39]
	v_mfma_f32_16x16x32_bf16 v[32:35], v[192:195], v[208:211], v[32:35]
	v_mfma_f32_16x16x32_bf16 v[20:23], v[184:187], v[216:219], v[20:23]
	v_mfma_f32_16x16x32_bf16 v[16:19], v[192:195], v[216:219], v[16:19]
	v_mfma_f32_16x16x32_bf16 v[4:7], v[184:187], v[224:227], v[4:7]
	v_mfma_f32_16x16x32_bf16 v[0:3], v[192:195], v[224:227], v[0:3]
	s_setprio 0
	s_barrier
	s_add_i32 s54, s54, 2
	s_add_u32 s52, s52, 0x1000
	s_addc_u32 s53, s53, 0
	s_cmp_gt_u32 s54, 61
	s_mov_b64 s[20:21], s[22:23]
	s_cbranch_scc0 .LBB0_1543
	s_and_b64 vcc, exec, s[4:5]
	s_cbranch_vccz .LBB0_1546
	s_barrier

.LBB0_1625:
	ds_read_b128 v[128:131], v177
	ds_read_b128 v[132:135], v177 offset:1024
	ds_read_b128 v[136:139], v177 offset:2048
	ds_read_b128 v[140:143], v177 offset:3072
	ds_read_b128 v[144:147], v178
	ds_read_b128 v[148:151], v178 offset:1024
	ds_read_b128 v[170:173], v178 offset:2048
	ds_read_b128 v[182:185], v178 offset:3072
	ds_read_b128 v[186:189], v179
	ds_read_b128 v[190:193], v179 offset:1024
	ds_read_b128 v[194:197], v179 offset:2048
	ds_read_b128 v[198:201], v179 offset:3072
	ds_read_b128 v[202:205], v179 offset:4096
	ds_read_b128 v[206:209], v179 offset:5120
	ds_read_b128 v[210:213], v179 offset:6144
	ds_read_b128 v[214:217], v179 offset:7168
	s_add_u32 s24, s22, 0xffc00800
	s_addc_u32 s25, s23, -1
	s_cmpk_eq_i32 s57, 0xfc
	s_cselect_b32 s27, s29, s25
	s_cselect_b32 s26, s53, s24
	s_cselect_b32 s25, s17, s56
	s_cselect_b32 s24, s54, s55
	v_lshl_add_u64 v[218:219], s[22:23], 0, v[162:163]
	s_add_i32 m0, s38, 0xc000
	s_nop 0
	global_load_lds_dwordx4 v[218:219], off
	v_lshl_add_u64 v[218:219], s[22:23], 0, v[164:165]
	s_add_i32 m0, s38, 0xe000
	s_nop 0
	global_load_lds_dwordx4 v[218:219], off
	s_waitcnt vmcnt(8)
	s_waitcnt lgkmcnt(0)
	s_setprio 1
	s_waitcnt lgkmcnt(0)
	v_mfma_f32_16x16x32_bf16 v[124:127], v[128:131], v[186:189], v[124:127]
	v_mfma_f32_16x16x32_bf16 v[120:123], v[136:139], v[186:189], v[120:123]
	v_mfma_f32_16x16x32_bf16 v[108:111], v[128:131], v[194:197], v[108:111]
	s_barrier
	v_mfma_f32_16x16x32_bf16 v[104:107], v[136:139], v[194:197], v[104:107]
	v_mfma_f32_16x16x32_bf16 v[92:95], v[128:131], v[202:205], v[92:95]
	v_mfma_f32_16x16x32_bf16 v[88:91], v[136:139], v[202:205], v[88:91]
	v_mfma_f32_16x16x32_bf16 v[76:79], v[128:131], v[210:213], v[76:79]
	v_mfma_f32_16x16x32_bf16 v[72:75], v[136:139], v[210:213], v[72:75]
	v_mfma_f32_16x16x32_bf16 v[124:127], v[132:135], v[190:193], v[124:127]
	v_mfma_f32_16x16x32_bf16 v[120:123], v[140:143], v[190:193], v[120:123]
	v_mfma_f32_16x16x32_bf16 v[108:111], v[132:135], v[198:201], v[108:111]
	v_mfma_f32_16x16x32_bf16 v[104:107], v[140:143], v[198:201], v[104:107]
	v_mfma_f32_16x16x32_bf16 v[92:95], v[132:135], v[206:209], v[92:95]
	v_mfma_f32_16x16x32_bf16 v[88:91], v[140:143], v[206:209], v[88:91]
	v_mfma_f32_16x16x32_bf16 v[76:79], v[132:135], v[214:217], v[76:79]
	v_mfma_f32_16x16x32_bf16 v[72:75], v[140:143], v[214:217], v[72:75]
	s_setprio 0
	s_setprio 1
	v_mfma_f32_16x16x32_bf16 v[116:119], v[144:147], v[186:189], v[116:119]
	v_mfma_f32_16x16x32_bf16 v[112:115], v[170:173], v[186:189], v[112:115]
	v_mfma_f32_16x16x32_bf16 v[100:103], v[144:147], v[194:197], v[100:103]
	v_mfma_f32_16x16x32_bf16 v[96:99], v[170:173], v[194:197], v[96:99]
	v_mfma_f32_16x16x32_bf16 v[84:87], v[144:147], v[202:205], v[84:87]
	v_mfma_f32_16x16x32_bf16 v[80:83], v[170:173], v[202:205], v[80:83]
	v_mfma_f32_16x16x32_bf16 v[68:71], v[144:147], v[210:213], v[68:71]
	v_mfma_f32_16x16x32_bf16 v[64:67], v[170:173], v[210:213], v[64:67]
	v_mfma_f32_16x16x32_bf16 v[116:119], v[148:151], v[190:193], v[116:119]
	v_mfma_f32_16x16x32_bf16 v[112:115], v[182:185], v[190:193], v[112:115]
	v_mfma_f32_16x16x32_bf16 v[100:103], v[148:151], v[198:201], v[100:103]
	v_mfma_f32_16x16x32_bf16 v[96:99], v[182:185], v[198:201], v[96:99]
	v_mfma_f32_16x16x32_bf16 v[84:87], v[148:151], v[206:209], v[84:87]
	v_mfma_f32_16x16x32_bf16 v[80:83], v[182:185], v[206:209], v[80:83]
	v_mfma_f32_16x16x32_bf16 v[68:71], v[148:151], v[214:217], v[68:71]
	v_mfma_f32_16x16x32_bf16 v[64:67], v[182:185], v[214:217], v[64:67]
	s_setprio 0
	s_barrier
	ds_read_b128 v[186:189], v179 offset:16384
	ds_read_b128 v[190:193], v179 offset:17408
	ds_read_b128 v[194:197], v179 offset:18432
	ds_read_b128 v[198:201], v179 offset:19456
	ds_read_b128 v[202:205], v179 offset:20480
	ds_read_b128 v[206:209], v179 offset:21504
	ds_read_b128 v[210:213], v179 offset:22528
	ds_read_b128 v[214:217], v179 offset:23552
	s_add_i32 s58, s48, s37
	v_lshl_add_u64 v[218:219], s[24:25], 0, v[154:155]
	s_mov_b32 m0, s58
	v_lshl_add_u64 v[220:221], s[24:25], 0, v[158:159]
	global_load_lds_dwordx4 v[218:219], off
	s_add_i32 m0, s58, 0x2000
	s_add_u32 s58, s24, 0x400000
	s_addc_u32 s59, s25, 0
	s_add_i32 s60, s49, s37
	global_load_lds_dwordx4 v[220:221], off
	s_mov_b32 m0, s60
	v_lshl_add_u64 v[222:223], s[26:27], 0, v[152:153]
	global_load_lds_dwordx4 v154, s[58:59]
	s_add_i32 m0, s60, 0x2000
	v_lshl_add_u64 v[224:225], s[26:27], 0, v[156:157]
	global_load_lds_dwordx4 v158, s[58:59]
	s_mov_b32 m0, s38
	s_nop 0
	global_load_lds_dwordx4 v[222:223], off
	s_mov_b32 m0, s39
	s_nop 0
	global_load_lds_dwordx4 v[224:225], off
	s_waitcnt vmcnt(8)
	s_waitcnt lgkmcnt(0)
	s_setprio 1
	s_waitcnt lgkmcnt(0)
	v_mfma_f32_16x16x32_bf16 v[60:63], v[128:131], v[186:189], v[60:63]
	v_mfma_f32_16x16x32_bf16 v[56:59], v[136:139], v[186:189], v[56:59]
	v_mfma_f32_16x16x32_bf16 v[44:47], v[128:131], v[194:197], v[44:47]
	s_barrier
	v_mfma_f32_16x16x32_bf16 v[40:43], v[136:139], v[194:197], v[40:43]
	v_mfma_f32_16x16x32_bf16 v[28:31], v[128:131], v[202:205], v[28:31]
	v_mfma_f32_16x16x32_bf16 v[24:27], v[136:139], v[202:205], v[24:27]
	v_mfma_f32_16x16x32_bf16 v[12:15], v[128:131], v[210:213], v[12:15]
	v_mfma_f32_16x16x32_bf16 v[8:11], v[136:139], v[210:213], v[8:11]
	v_mfma_f32_16x16x32_bf16 v[60:63], v[132:135], v[190:193], v[60:63]
	v_mfma_f32_16x16x32_bf16 v[56:59], v[140:143], v[190:193], v[56:59]
	v_mfma_f32_16x16x32_bf16 v[44:47], v[132:135], v[198:201], v[44:47]
	v_mfma_f32_16x16x32_bf16 v[40:43], v[140:143], v[198:201], v[40:43]
	v_mfma_f32_16x16x32_bf16 v[28:31], v[132:135], v[206:209], v[28:31]
	v_mfma_f32_16x16x32_bf16 v[24:27], v[140:143], v[206:209], v[24:27]
	v_mfma_f32_16x16x32_bf16 v[12:15], v[132:135], v[214:217], v[12:15]
	v_mfma_f32_16x16x32_bf16 v[8:11], v[140:143], v[214:217], v[8:11]
	s_setprio 0
	s_setprio 1
	v_mfma_f32_16x16x32_bf16 v[52:55], v[144:147], v[186:189], v[52:55]
	v_mfma_f32_16x16x32_bf16 v[48:51], v[170:173], v[186:189], v[48:51]
	v_mfma_f32_16x16x32_bf16 v[36:39], v[144:147], v[194:197], v[36:39]
	v_mfma_f32_16x16x32_bf16 v[32:35], v[170:173], v[194:197], v[32:35]
	v_mfma_f32_16x16x32_bf16 v[20:23], v[144:147], v[202:205], v[20:23]
	v_mfma_f32_16x16x32_bf16 v[16:19], v[170:173], v[202:205], v[16:19]
	v_mfma_f32_16x16x32_bf16 v[4:7], v[144:147], v[210:213], v[4:7]
	v_mfma_f32_16x16x32_bf16 v[0:3], v[170:173], v[210:213], v[0:3]
	v_mfma_f32_16x16x32_bf16 v[52:55], v[148:151], v[190:193], v[52:55]
	v_mfma_f32_16x16x32_bf16 v[48:51], v[182:185], v[190:193], v[48:51]
	v_mfma_f32_16x16x32_bf16 v[36:39], v[148:151], v[198:201], v[36:39]
	v_mfma_f32_16x16x32_bf16 v[32:35], v[182:185], v[198:201], v[32:35]
	v_mfma_f32_16x16x32_bf16 v[20:23], v[148:151], v[206:209], v[20:23]
	v_mfma_f32_16x16x32_bf16 v[16:19], v[182:185], v[206:209], v[16:19]
	v_mfma_f32_16x16x32_bf16 v[4:7], v[148:151], v[214:217], v[4:7]
	v_mfma_f32_16x16x32_bf16 v[0:3], v[182:185], v[214:217], v[0:3]
	s_setprio 0
	s_barrier
	s_add_i32 s58, 0, 0x18000
	s_add_i32 s59, 0, 0x1c000
	v_add_u32_e32 v140, s58, v174
	v_add_u32_e32 v181, s59, v174
	ds_read_b128 v[128:131], v140
	ds_read_b128 v[132:135], v140 offset:1024
	ds_read_b128 v[136:139], v140 offset:2048
	ds_read_b128 v[140:143], v140 offset:3072
	ds_read_b128 v[144:147], v181
	ds_read_b128 v[148:151], v181 offset:1024
	ds_read_b128 v[170:173], v181 offset:2048
	ds_read_b128 v[182:185], v181 offset:3072
	ds_read_b128 v[186:189], v179 offset:32768
	ds_read_b128 v[190:193], v179 offset:33792
	ds_read_b128 v[194:197], v179 offset:34816
	ds_read_b128 v[198:201], v179 offset:35840
	ds_read_b128 v[202:205], v179 offset:36864
	ds_read_b128 v[206:209], v179 offset:37888
	ds_read_b128 v[210:213], v179 offset:38912
	ds_read_b128 v[214:217], v179 offset:39936
	s_add_u32 s26, s26, 0x400000
	s_addc_u32 s27, s27, 0
	s_mov_b32 m0, s40
	s_nop 0
	global_load_lds_dwordx4 v152, s[26:27]
	s_mov_b32 m0, s41
	s_nop 0
	global_load_lds_dwordx4 v156, s[26:27]
	s_waitcnt vmcnt(8)
	s_waitcnt lgkmcnt(0)
	s_setprio 1
	s_waitcnt lgkmcnt(0)
	v_mfma_f32_16x16x32_bf16 v[124:127], v[128:131], v[186:189], v[124:127]
	v_mfma_f32_16x16x32_bf16 v[120:123], v[136:139], v[186:189], v[120:123]
	v_mfma_f32_16x16x32_bf16 v[108:111], v[128:131], v[194:197], v[108:111]
	s_barrier
	v_mfma_f32_16x16x32_bf16 v[104:107], v[136:139], v[194:197], v[104:107]
	v_mfma_f32_16x16x32_bf16 v[92:95], v[128:131], v[202:205], v[92:95]
	v_mfma_f32_16x16x32_bf16 v[88:91], v[136:139], v[202:205], v[88:91]
	v_mfma_f32_16x16x32_bf16 v[76:79], v[128:131], v[210:213], v[76:79]
	v_mfma_f32_16x16x32_bf16 v[72:75], v[136:139], v[210:213], v[72:75]
	v_mfma_f32_16x16x32_bf16 v[124:127], v[132:135], v[190:193], v[124:127]
	v_mfma_f32_16x16x32_bf16 v[120:123], v[140:143], v[190:193], v[120:123]
	v_mfma_f32_16x16x32_bf16 v[108:111], v[132:135], v[198:201], v[108:111]
	v_mfma_f32_16x16x32_bf16 v[104:107], v[140:143], v[198:201], v[104:107]
	v_mfma_f32_16x16x32_bf16 v[92:95], v[132:135], v[206:209], v[92:95]
	v_mfma_f32_16x16x32_bf16 v[88:91], v[140:143], v[206:209], v[88:91]
	v_mfma_f32_16x16x32_bf16 v[76:79], v[132:135], v[214:217], v[76:79]
	v_mfma_f32_16x16x32_bf16 v[72:75], v[140:143], v[214:217], v[72:75]
	s_setprio 0
	s_setprio 1
	v_mfma_f32_16x16x32_bf16 v[116:119], v[144:147], v[186:189], v[116:119]
	v_mfma_f32_16x16x32_bf16 v[112:115], v[170:173], v[186:189], v[112:115]
	v_mfma_f32_16x16x32_bf16 v[100:103], v[144:147], v[194:197], v[100:103]
	v_mfma_f32_16x16x32_bf16 v[96:99], v[170:173], v[194:197], v[96:99]
	v_mfma_f32_16x16x32_bf16 v[84:87], v[144:147], v[202:205], v[84:87]
	v_mfma_f32_16x16x32_bf16 v[80:83], v[170:173], v[202:205], v[80:83]
	v_mfma_f32_16x16x32_bf16 v[68:71], v[144:147], v[210:213], v[68:71]
	v_mfma_f32_16x16x32_bf16 v[64:67], v[170:173], v[210:213], v[64:67]
	v_mfma_f32_16x16x32_bf16 v[116:119], v[148:151], v[190:193], v[116:119]
	v_mfma_f32_16x16x32_bf16 v[112:115], v[182:185], v[190:193], v[112:115]
	v_mfma_f32_16x16x32_bf16 v[100:103], v[148:151], v[198:201], v[100:103]
	v_mfma_f32_16x16x32_bf16 v[96:99], v[182:185], v[198:201], v[96:99]
	v_mfma_f32_16x16x32_bf16 v[84:87], v[148:151], v[206:209], v[84:87]
	v_mfma_f32_16x16x32_bf16 v[80:83], v[182:185], v[206:209], v[80:83]
	v_mfma_f32_16x16x32_bf16 v[68:71], v[148:151], v[214:217], v[68:71]
	v_mfma_f32_16x16x32_bf16 v[64:67], v[182:185], v[214:217], v[64:67]
	s_setprio 0
	s_barrier
	ds_read_b128 v[186:189], v179 offset:49152
	ds_read_b128 v[190:193], v179 offset:50176
	ds_read_b128 v[194:197], v179 offset:51200
	ds_read_b128 v[198:201], v179 offset:52224
	ds_read_b128 v[202:205], v179 offset:53248
	ds_read_b128 v[206:209], v179 offset:54272
	ds_read_b128 v[210:213], v179 offset:55296
	ds_read_b128 v[214:217], v179 offset:56320
	s_add_i32 s26, s58, s37
	v_lshl_add_u64 v[218:219], v[218:219], 0, s[14:15]
	s_mov_b32 m0, s26
	s_nop 0
	global_load_lds_dwordx4 v[218:219], off
	s_add_i32 m0, s26, 0x2000
	s_add_u32 s24, s24, 0x400800
	v_lshl_add_u64 v[220:221], v[220:221], 0, s[14:15]
	s_addc_u32 s25, s25, 0
	s_add_i32 s26, s59, s37
	global_load_lds_dwordx4 v[220:221], off
	s_mov_b32 m0, s26
	s_nop 0
	global_load_lds_dwordx4 v154, s[24:25]
	s_add_i32 m0, s26, 0x2000
	s_nop 0
	global_load_lds_dwordx4 v158, s[24:25]
	v_lshl_add_u64 v[222:223], v[222:223], 0, s[14:15]
	s_mov_b32 m0, s43
	s_nop 0
	global_load_lds_dwordx4 v[222:223], off
	v_lshl_add_u64 v[224:225], v[224:225], 0, s[14:15]
	s_mov_b32 m0, s44
	s_nop 0
	global_load_lds_dwordx4 v[224:225], off
	s_waitcnt vmcnt(8)
	s_waitcnt lgkmcnt(0)
	s_setprio 1
	s_waitcnt lgkmcnt(0)
	v_mfma_f32_16x16x32_bf16 v[60:63], v[128:131], v[186:189], v[60:63]
	v_mfma_f32_16x16x32_bf16 v[56:59], v[136:139], v[186:189], v[56:59]
	v_mfma_f32_16x16x32_bf16 v[44:47], v[128:131], v[194:197], v[44:47]
	s_barrier
	v_mfma_f32_16x16x32_bf16 v[40:43], v[136:139], v[194:197], v[40:43]
	v_mfma_f32_16x16x32_bf16 v[28:31], v[128:131], v[202:205], v[28:31]
	v_mfma_f32_16x16x32_bf16 v[24:27], v[136:139], v[202:205], v[24:27]
	v_mfma_f32_16x16x32_bf16 v[12:15], v[128:131], v[210:213], v[12:15]
	v_mfma_f32_16x16x32_bf16 v[8:11], v[136:139], v[210:213], v[8:11]
	v_mfma_f32_16x16x32_bf16 v[60:63], v[132:135], v[190:193], v[60:63]
	v_mfma_f32_16x16x32_bf16 v[56:59], v[140:143], v[190:193], v[56:59]
	v_mfma_f32_16x16x32_bf16 v[44:47], v[132:135], v[198:201], v[44:47]
	v_mfma_f32_16x16x32_bf16 v[40:43], v[140:143], v[198:201], v[40:43]
	v_mfma_f32_16x16x32_bf16 v[28:31], v[132:135], v[206:209], v[28:31]
	v_mfma_f32_16x16x32_bf16 v[24:27], v[140:143], v[206:209], v[24:27]
	v_mfma_f32_16x16x32_bf16 v[12:15], v[132:135], v[214:217], v[12:15]
	v_mfma_f32_16x16x32_bf16 v[8:11], v[140:143], v[214:217], v[8:11]
	s_setprio 0
	s_setprio 1
	v_mfma_f32_16x16x32_bf16 v[52:55], v[144:147], v[186:189], v[52:55]
	v_mfma_f32_16x16x32_bf16 v[48:51], v[170:173], v[186:189], v[48:51]
	v_mfma_f32_16x16x32_bf16 v[36:39], v[144:147], v[194:197], v[36:39]
	v_mfma_f32_16x16x32_bf16 v[32:35], v[170:173], v[194:197], v[32:35]
	v_mfma_f32_16x16x32_bf16 v[20:23], v[144:147], v[202:205], v[20:23]
	v_mfma_f32_16x16x32_bf16 v[16:19], v[170:173], v[202:205], v[16:19]
	v_mfma_f32_16x16x32_bf16 v[4:7], v[144:147], v[210:213], v[4:7]
	v_mfma_f32_16x16x32_bf16 v[0:3], v[170:173], v[210:213], v[0:3]
	v_mfma_f32_16x16x32_bf16 v[52:55], v[148:151], v[190:193], v[52:55]
	v_mfma_f32_16x16x32_bf16 v[48:51], v[182:185], v[190:193], v[48:51]
	v_mfma_f32_16x16x32_bf16 v[36:39], v[148:151], v[198:201], v[36:39]
	v_mfma_f32_16x16x32_bf16 v[32:35], v[182:185], v[198:201], v[32:35]
	v_mfma_f32_16x16x32_bf16 v[20:23], v[148:151], v[206:209], v[20:23]
	v_mfma_f32_16x16x32_bf16 v[16:19], v[182:185], v[206:209], v[16:19]
	v_mfma_f32_16x16x32_bf16 v[4:7], v[148:151], v[214:217], v[4:7]
	v_mfma_f32_16x16x32_bf16 v[0:3], v[182:185], v[214:217], v[0:3]
	s_setprio 0
	s_barrier
	s_add_i32 s57, s57, 2
	s_add_u32 s22, s22, 0x1000
	s_addc_u32 s23, s23, 0
	s_add_u32 s55, s55, 0x1000
	s_addc_u32 s56, s56, 0
	s_cmpk_gt_u32 s57, 0xfd
	s_cbranch_scc0 .LBB0_1625
	s_and_b64 vcc, exec, s[6:7]
	s_cbranch_vccz .LBB0_1628
	s_barrier
